# stack2: + FFN gate/up K-loop stage rebalancing, per-phase vmcnt(10) waits in the other seven K-loops, prologue vmcnt moved behind the accumulator zero-init
# baseline (speedup 1.0000x reference)
; #define WAIT_V8(n) asm volatile("s_waitcnt vmcnt(" #n ")" ::: "memory")
; #define BAR8 __builtin_amdgcn_s_barrier()
;     ...
;   const int brow = m0, bcol = n0;
;   const int wid = t >> 6, lane = t & 63, wr = wid >> 2, wc = wid & 3, fr = lane & 15, fq = lane >> 4;
;   f32x4 acc[2][2][4][2];
;   {
;     float zinit = 0.f;
;     asm volatile("" : "+v"(zinit));
; #pragma unroll
;     for (int a = 0; a < 2; ++a)
; #pragma unroll
;       for (int b = 0; b < 2; ++b)
; #pragma unroll
;         for (int m = 0; m < 4; ++m)
; #pragma unroll
;           for (int n = 0; n < 2; ++n)
; #pragma unroll
;             for (int j = 0; j < 4; ++j) acc[a][b][m][n][j] = zinit;
;   }
;   bf16x8 At[4][2], B0[2][2], B1[2][2];
;   const int nt = K / 64;
;   if (!pre) {
;     STAGE8(SB8(0, 0), Bt, K, bcol, 0); STAGE8(SA8(0, 0), A, lda, brow, 0);
;     STAGE8(SB8(0, 1), Bt, K, bcol + 128, 0); STAGE8(SA8(0, 1), A, lda, brow + 128, 0);
;   }
;   if (wr == 1) BAR8;
;   WAIT_V8(4); BAR8;
;   STAGE8(SB8(1, 0), Bt, K, bcol, 1); STAGE8(SA8(1, 0), A, lda, brow, 1); STAGE8(SB8(1, 1), Bt, K, bcol + 128, 1);
;   WAIT_V8(6); BAR8;
.LBB0_191:
	s_or_b64 exec, exec, s[14:15]
	v_add_u32_e32 v164, 0x18000, v150
	s_mov_b64 s[60:61], 0x80
	v_readfirstlane_b32 s14, v164
	v_add_u32_e32 v165, 0x1a000, v150
	v_lshl_add_u64 v[10:11], v[10:11], 0, s[60:61]
	s_mov_b32 m0, s14
	v_readfirstlane_b32 s14, v165
	v_add_u32_e32 v166, 0x8000, v150
	s_waitcnt vmcnt(4)
	s_barrier
	global_load_lds_dwordx4 v[10:11], off
	v_lshl_add_u64 v[10:11], v[12:13], 0, s[60:61]
	s_mov_b32 m0, s14
	v_readfirstlane_b32 s14, v166
	v_add_u32_e32 v167, 0xa000, v150
	global_load_lds_dwordx4 v[10:11], off
	v_lshl_add_u64 v[10:11], v[14:15], 0, s[60:61]
	s_mov_b32 m0, s14
	v_readfirstlane_b32 s14, v167
	v_add_u32_e32 v168, 0x1c000, v150
	global_load_lds_dwordx4 v[10:11], off
	v_lshl_add_u64 v[10:11], v[16:17], 0, s[60:61]
	s_mov_b32 m0, s14
	v_readfirstlane_b32 s14, v168
	v_add_u32_e32 v170, 0x1e000, v150
	global_load_lds_dwordx4 v[10:11], off
	v_lshl_add_u64 v[10:11], v[18:19], 0, s[60:61]
	s_mov_b32 m0, s14
	v_readfirstlane_b32 s14, v170
	global_load_lds_dwordx4 v[10:11], off
	v_lshl_add_u64 v[10:11], v[20:21], 0, s[60:61]
	s_mov_b32 m0, s14
	v_and_b32_e32 v147, 15, v3
	global_load_lds_dwordx4 v[10:11], off
	v_bfe_u32 v148, v3, 4, 2
	v_lshlrev_b32_e32 v10, 4, v148
	v_lshlrev_b32_e32 v11, 6, v147
	v_lshlrev_b32_e32 v14, 2, v3
	v_or_b32_e32 v13, v10, v11
	v_and_b32_e32 v14, 32, v14
	s_mov_b32 s14, 0x10000
	v_bitop3_b32 v16, v13, s14, v14 bitop3:0xde
	s_mov_b32 s14, 0x14000
	v_bitop3_b32 v15, v10, v14, v11 bitop3:0x36
	v_bitop3_b32 v17, v13, s14, v14 bitop3:0xde
	s_mov_b32 s14, 0x18000
	v_lshlrev_b32_e32 v11, 6, v3
	v_bitop3_b32 v18, v13, s14, v14 bitop3:0xde
	s_mov_b32 s14, 0x1c000
	v_and_b32_e32 v11, 0x3c0, v11
	v_bitop3_b32 v13, v13, s14, v14 bitop3:0xde
	v_bitop3_b32 v14, v11, v14, v10 bitop3:0x36
	v_lshl_add_u64 v[10:11], s[30:31], 0, v[136:137]
	v_lshl_add_u64 v[10:11], v[10:11], 0, v[8:9]
	v_lshl_add_u64 v[138:139], s[12:13], 0, v[10:11]
	v_lshl_add_u64 v[10:11], s[30:31], 0, v[132:133]
	v_lshl_add_u64 v[10:11], v[10:11], 0, v[6:7]
	v_lshl_add_u64 v[140:141], s[12:13], 0, v[10:11]
	v_lshl_add_u64 v[10:11], s[56:57], 0, v[132:133]
	v_lshl_add_u64 v[6:7], v[10:11], 0, v[6:7]
	v_bfe_u32 v146, v3, 6, 2
	v_lshlrev_b32_e32 v149, 6, v5
	v_lshlrev_b32_e32 v5, 13, v5
	v_lshl_add_u64 v[142:143], s[46:47], 0, v[6:7]
	v_lshl_add_u64 v[6:7], s[56:57], 0, v[136:137]
	v_lshlrev_b32_e32 v12, 12, v146
	v_or_b32_e32 v19, 0x800, v5
	v_or_b32_e32 v20, 0x1000, v5
	v_or_b32_e32 v21, 0x1800, v5
	v_lshl_add_u64 v[6:7], v[6:7], 0, v[8:9]
	v_lshl_add_u64 v[144:145], s[46:47], 0, v[6:7]
	s_mov_b32 s14, -2
	s_mov_b64 s[12:13], 0
	v_add_u32_e32 v173, v16, v12
	v_add_u32_e32 v156, v15, v5
	v_add_u32_e32 v154, v14, v19
	v_add_u32_e32 v153, v14, v20
	v_add_u32_e32 v152, v14, v21
	v_add_u32_e32 v172, 0xc000, v150
	v_add_u32_e32 v171, 0xe000, v150
	v_add_u32_e32 v169, v17, v12
	v_add_u32_e32 v159, v18, v12
	v_add_u32_e32 v158, v13, v12
	v_mov_b32_e32 v5, v4
	v_mov_b32_e32 v6, v4
	v_mov_b32_e32 v7, v4
	v_mov_b32_e32 v8, v4
	v_mov_b32_e32 v9, v4
	v_mov_b32_e32 v10, v4
	v_mov_b32_e32 v11, v4
	v_mov_b32_e32 v12, v4
	v_mov_b32_e32 v13, v4
	v_mov_b32_e32 v14, v4
	v_mov_b32_e32 v15, v4
	v_mov_b32_e32 v16, v4
	v_mov_b32_e32 v17, v4
	v_mov_b32_e32 v18, v4
	v_mov_b32_e32 v19, v4
	v_mov_b32_e32 v20, v4
	v_mov_b32_e32 v21, v4
	v_mov_b32_e32 v22, v4
	v_mov_b32_e32 v23, v4
	v_mov_b32_e32 v24, v4
	v_mov_b32_e32 v25, v4
	v_mov_b32_e32 v26, v4
	v_mov_b32_e32 v27, v4
	v_mov_b32_e32 v28, v4
	v_mov_b32_e32 v29, v4
	v_mov_b32_e32 v30, v4
	v_mov_b32_e32 v31, v4
	v_mov_b32_e32 v32, v4
	v_mov_b32_e32 v33, v4
	v_mov_b32_e32 v34, v4
	v_mov_b32_e32 v35, v4
	v_mov_b32_e32 v36, v4
	v_mov_b32_e32 v37, v4
	v_mov_b32_e32 v38, v4
	v_mov_b32_e32 v39, v4
	v_mov_b32_e32 v40, v4
	v_mov_b32_e32 v41, v4
	v_mov_b32_e32 v42, v4
	v_mov_b32_e32 v43, v4
	v_mov_b32_e32 v44, v4
	v_mov_b32_e32 v45, v4
	v_mov_b32_e32 v46, v4
	v_mov_b32_e32 v47, v4
	v_mov_b32_e32 v48, v4
	v_mov_b32_e32 v49, v4
	v_mov_b32_e32 v50, v4
	v_mov_b32_e32 v51, v4
	v_mov_b32_e32 v52, v4
	v_mov_b32_e32 v53, v4
	v_mov_b32_e32 v54, v4
	v_mov_b32_e32 v55, v4
	v_mov_b32_e32 v56, v4
	v_mov_b32_e32 v57, v4
	v_mov_b32_e32 v58, v4
	v_mov_b32_e32 v59, v4
	v_mov_b32_e32 v60, v4
	v_mov_b32_e32 v61, v4
	v_mov_b32_e32 v62, v4
	v_mov_b32_e32 v63, v4
	v_mov_b32_e32 v64, v4
	v_mov_b32_e32 v65, v4
	v_mov_b32_e32 v66, v4
	v_mov_b32_e32 v67, v4
	v_mov_b32_e32 v68, v4
	v_mov_b32_e32 v69, v4
	v_mov_b32_e32 v70, v4
	v_mov_b32_e32 v71, v4
	v_mov_b32_e32 v72, v4
	v_mov_b32_e32 v73, v4
	v_mov_b32_e32 v74, v4
	v_mov_b32_e32 v75, v4
	v_mov_b32_e32 v76, v4
	v_mov_b32_e32 v77, v4
	v_mov_b32_e32 v78, v4
	v_mov_b32_e32 v79, v4
	v_mov_b32_e32 v80, v4
	v_mov_b32_e32 v81, v4
	v_mov_b32_e32 v82, v4
	v_mov_b32_e32 v83, v4
	v_mov_b32_e32 v84, v4
	v_mov_b32_e32 v85, v4
	v_mov_b32_e32 v86, v4
	v_mov_b32_e32 v87, v4
	v_mov_b32_e32 v88, v4
	v_mov_b32_e32 v89, v4
	v_mov_b32_e32 v90, v4
	v_mov_b32_e32 v91, v4
	v_mov_b32_e32 v92, v4
	v_mov_b32_e32 v93, v4
	v_mov_b32_e32 v94, v4
	v_mov_b32_e32 v95, v4
	v_mov_b32_e32 v96, v4
	v_mov_b32_e32 v97, v4
	v_mov_b32_e32 v98, v4
	v_mov_b32_e32 v99, v4
	v_mov_b32_e32 v100, v4
	v_mov_b32_e32 v101, v4
	v_mov_b32_e32 v102, v4
	v_mov_b32_e32 v103, v4
	v_mov_b32_e32 v104, v4
	v_mov_b32_e32 v105, v4
	v_mov_b32_e32 v106, v4
	v_mov_b32_e32 v107, v4
	v_mov_b32_e32 v108, v4
	v_mov_b32_e32 v109, v4
	v_mov_b32_e32 v110, v4
	v_mov_b32_e32 v111, v4
	v_mov_b32_e32 v112, v4
	v_mov_b32_e32 v113, v4
	v_mov_b32_e32 v114, v4
	v_mov_b32_e32 v115, v4
	v_mov_b32_e32 v116, v4
	v_mov_b32_e32 v117, v4
	v_mov_b32_e32 v118, v4
	v_mov_b32_e32 v119, v4
	v_mov_b32_e32 v120, v4
	v_mov_b32_e32 v121, v4
	v_mov_b32_e32 v122, v4
	v_mov_b32_e32 v123, v4
	v_mov_b32_e32 v124, v4
	v_mov_b32_e32 v125, v4
	v_mov_b32_e32 v126, v4
	v_mov_b32_e32 v127, v4
	v_mov_b32_e32 v128, v4
	v_mov_b32_e32 v129, v4
	v_mov_b32_e32 v130, v4
	v_mov_b32_e32 v131, v4
	s_mov_b64 s[60:61], 0xc000100
	s_mov_b64 s[62:63], 0xc040100
	s_mov_b64 s[64:65], 0xc000180
	s_mov_b64 s[66:67], 0xc040180
	s_waitcnt vmcnt(6)
	s_barrier

; #define WAIT_V8(n) asm volatile("s_waitcnt vmcnt(" #n ")" ::: "memory")
; #define BAR8 __builtin_amdgcn_s_barrier()
;     ...
;   const int brow = m0, bcol = n0;
;   const int wid = t >> 6, lane = t & 63, wr = wid >> 2, wc = wid & 3, fr = lane & 15, fq = lane >> 4;
;   f32x4 acc[2][2][4][2];
;   {
;     float zinit = 0.f;
;     asm volatile("" : "+v"(zinit));
; #pragma unroll
;     for (int a = 0; a < 2; ++a)
; #pragma unroll
;       for (int b = 0; b < 2; ++b)
; #pragma unroll
;         for (int m = 0; m < 4; ++m)
; #pragma unroll
;           for (int n = 0; n < 2; ++n)
; #pragma unroll
;             for (int j = 0; j < 4; ++j) acc[a][b][m][n][j] = zinit;
;   }
;   bf16x8 At[4][2], B0[2][2], B1[2][2];
;   const int nt = K / 64;
;   if (!pre) {
;     STAGE8(SB8(0, 0), Bt, K, bcol, 0); STAGE8(SA8(0, 0), A, lda, brow, 0);
;     STAGE8(SB8(0, 1), Bt, K, bcol + 128, 0); STAGE8(SA8(0, 1), A, lda, brow + 128, 0);
;   }
;   if (wr == 1) BAR8;
;   WAIT_V8(4); BAR8;
;   STAGE8(SB8(1, 0), Bt, K, bcol, 1); STAGE8(SA8(1, 0), A, lda, brow, 1); STAGE8(SB8(1, 1), Bt, K, bcol + 128, 1);
;   WAIT_V8(6); BAR8;
.LBB0_241:
	s_or_b64 exec, exec, s[20:21]
	v_add_u32_e32 v164, 0x18000, v150
	s_mov_b64 s[20:21], 0x80
	v_readfirstlane_b32 s1, v164
	v_add_u32_e32 v165, 0x1a000, v150
	v_lshl_add_u64 v[10:11], v[10:11], 0, s[20:21]
	s_mov_b32 m0, s1
	v_readfirstlane_b32 s1, v165
	v_add_u32_e32 v166, 0x8000, v150
	s_waitcnt vmcnt(4)
	s_barrier
	global_load_lds_dwordx4 v[10:11], off
	v_lshl_add_u64 v[10:11], v[12:13], 0, s[20:21]
	s_mov_b32 m0, s1
	v_readfirstlane_b32 s1, v166
	v_add_u32_e32 v167, 0xa000, v150
	global_load_lds_dwordx4 v[10:11], off
	v_lshl_add_u64 v[10:11], v[14:15], 0, s[20:21]
	s_mov_b32 m0, s1
	v_readfirstlane_b32 s1, v167
	v_add_u32_e32 v169, 0x1c000, v150
	global_load_lds_dwordx4 v[10:11], off
	v_lshl_add_u64 v[10:11], v[16:17], 0, s[20:21]
	s_mov_b32 m0, s1
	v_readfirstlane_b32 s1, v169
	v_add_u32_e32 v170, 0x1e000, v150
	global_load_lds_dwordx4 v[10:11], off
	v_lshl_add_u64 v[10:11], v[18:19], 0, s[20:21]
	s_mov_b32 m0, s1
	v_readfirstlane_b32 s1, v170
	global_load_lds_dwordx4 v[10:11], off
	v_lshl_add_u64 v[10:11], v[20:21], 0, s[20:21]
	s_mov_b32 m0, s1
	v_and_b32_e32 v147, 15, v3
	global_load_lds_dwordx4 v[10:11], off
	v_bfe_u32 v148, v3, 4, 2
	v_lshlrev_b32_e32 v10, 4, v148
	v_lshlrev_b32_e32 v11, 6, v147
	v_lshlrev_b32_e32 v14, 2, v3
	v_or_b32_e32 v13, v10, v11
	v_and_b32_e32 v14, 32, v14
	s_mov_b32 s1, 0x10000
	v_bitop3_b32 v16, v13, s1, v14 bitop3:0xde
	s_mov_b32 s1, 0x14000
	v_bitop3_b32 v15, v10, v14, v11 bitop3:0x36
	v_bitop3_b32 v17, v13, s1, v14 bitop3:0xde
	s_mov_b32 s1, 0x18000
	v_lshlrev_b32_e32 v11, 6, v3
	v_bitop3_b32 v18, v13, s1, v14 bitop3:0xde
	s_mov_b32 s1, 0x1c000
	v_and_b32_e32 v11, 0x3c0, v11
	v_bitop3_b32 v13, v13, s1, v14 bitop3:0xde
	v_bitop3_b32 v14, v11, v14, v10 bitop3:0x36
	v_lshl_add_u64 v[10:11], s[30:31], 0, v[136:137]
	v_lshl_add_u64 v[10:11], v[10:11], 0, v[8:9]
	v_lshl_add_u64 v[138:139], s[14:15], 0, v[10:11]
	v_lshl_add_u64 v[10:11], s[30:31], 0, v[132:133]
	v_lshl_add_u64 v[10:11], v[10:11], 0, v[6:7]
	v_lshl_add_u64 v[140:141], s[14:15], 0, v[10:11]
	v_lshl_add_u64 v[10:11], s[56:57], 0, v[132:133]
	v_lshl_add_u64 v[6:7], v[10:11], 0, v[6:7]
	v_bfe_u32 v146, v3, 6, 2
	v_lshlrev_b32_e32 v149, 6, v5
	v_lshlrev_b32_e32 v5, 13, v5
	v_lshl_add_u64 v[142:143], s[46:47], 0, v[6:7]
	v_lshl_add_u64 v[6:7], s[56:57], 0, v[136:137]
	v_lshlrev_b32_e32 v12, 12, v146
	v_or_b32_e32 v19, 0x800, v5
	v_or_b32_e32 v20, 0x1000, v5
	v_or_b32_e32 v21, 0x1800, v5
	v_lshl_add_u64 v[6:7], v[6:7], 0, v[8:9]
	v_lshl_add_u64 v[144:145], s[46:47], 0, v[6:7]
	s_mov_b32 s1, -2
	s_mov_b64 s[14:15], 0
	v_add_u32_e32 v171, v16, v12
	v_add_u32_e32 v156, v15, v5
	v_add_u32_e32 v154, v14, v19
	v_add_u32_e32 v153, v14, v20
	v_add_u32_e32 v152, v14, v21
	v_add_u32_e32 v168, v17, v12
	v_add_u32_e32 v159, v18, v12
	v_add_u32_e32 v157, v13, v12
	v_mov_b32_e32 v5, v4
	v_mov_b32_e32 v6, v4
	v_mov_b32_e32 v7, v4
	v_mov_b32_e32 v8, v4
	v_mov_b32_e32 v9, v4
	v_mov_b32_e32 v10, v4
	v_mov_b32_e32 v11, v4
	v_mov_b32_e32 v12, v4
	v_mov_b32_e32 v13, v4
	v_mov_b32_e32 v14, v4
	v_mov_b32_e32 v15, v4
	v_mov_b32_e32 v16, v4
	v_mov_b32_e32 v17, v4
	v_mov_b32_e32 v18, v4
	v_mov_b32_e32 v19, v4
	v_mov_b32_e32 v20, v4
	v_mov_b32_e32 v21, v4
	v_mov_b32_e32 v22, v4
	v_mov_b32_e32 v23, v4
	v_mov_b32_e32 v24, v4
	v_mov_b32_e32 v25, v4
	v_mov_b32_e32 v26, v4
	v_mov_b32_e32 v27, v4
	v_mov_b32_e32 v28, v4
	v_mov_b32_e32 v29, v4
	v_mov_b32_e32 v30, v4
	v_mov_b32_e32 v31, v4
	v_mov_b32_e32 v32, v4
	v_mov_b32_e32 v33, v4
	v_mov_b32_e32 v34, v4
	v_mov_b32_e32 v35, v4
	v_mov_b32_e32 v36, v4
	v_mov_b32_e32 v37, v4
	v_mov_b32_e32 v38, v4
	v_mov_b32_e32 v39, v4
	v_mov_b32_e32 v40, v4
	v_mov_b32_e32 v41, v4
	v_mov_b32_e32 v42, v4
	v_mov_b32_e32 v43, v4
	v_mov_b32_e32 v44, v4
	v_mov_b32_e32 v45, v4
	v_mov_b32_e32 v46, v4
	v_mov_b32_e32 v47, v4
	v_mov_b32_e32 v48, v4
	v_mov_b32_e32 v49, v4
	v_mov_b32_e32 v50, v4
	v_mov_b32_e32 v51, v4
	v_mov_b32_e32 v52, v4
	v_mov_b32_e32 v53, v4
	v_mov_b32_e32 v54, v4
	v_mov_b32_e32 v55, v4
	v_mov_b32_e32 v56, v4
	v_mov_b32_e32 v57, v4
	v_mov_b32_e32 v58, v4
	v_mov_b32_e32 v59, v4
	v_mov_b32_e32 v60, v4
	v_mov_b32_e32 v61, v4
	v_mov_b32_e32 v62, v4
	v_mov_b32_e32 v63, v4
	v_mov_b32_e32 v64, v4
	v_mov_b32_e32 v65, v4
	v_mov_b32_e32 v66, v4
	v_mov_b32_e32 v67, v4
	v_mov_b32_e32 v68, v4
	v_mov_b32_e32 v69, v4
	v_mov_b32_e32 v70, v4
	v_mov_b32_e32 v71, v4
	v_mov_b32_e32 v72, v4
	v_mov_b32_e32 v73, v4
	v_mov_b32_e32 v74, v4
	v_mov_b32_e32 v75, v4
	v_mov_b32_e32 v76, v4
	v_mov_b32_e32 v77, v4
	v_mov_b32_e32 v78, v4
	v_mov_b32_e32 v79, v4
	v_mov_b32_e32 v80, v4
	v_mov_b32_e32 v81, v4
	v_mov_b32_e32 v82, v4
	v_mov_b32_e32 v83, v4
	v_mov_b32_e32 v84, v4
	v_mov_b32_e32 v85, v4
	v_mov_b32_e32 v86, v4
	v_mov_b32_e32 v87, v4
	v_mov_b32_e32 v88, v4
	v_mov_b32_e32 v89, v4
	v_mov_b32_e32 v90, v4
	v_mov_b32_e32 v91, v4
	v_mov_b32_e32 v92, v4
	v_mov_b32_e32 v93, v4
	v_mov_b32_e32 v94, v4
	v_mov_b32_e32 v95, v4
	v_mov_b32_e32 v96, v4
	v_mov_b32_e32 v97, v4
	v_mov_b32_e32 v98, v4
	v_mov_b32_e32 v99, v4
	v_mov_b32_e32 v100, v4
	v_mov_b32_e32 v101, v4
	v_mov_b32_e32 v102, v4
	v_mov_b32_e32 v103, v4
	v_mov_b32_e32 v104, v4
	v_mov_b32_e32 v105, v4
	v_mov_b32_e32 v106, v4
	v_mov_b32_e32 v107, v4
	v_mov_b32_e32 v108, v4
	v_mov_b32_e32 v109, v4
	v_mov_b32_e32 v110, v4
	v_mov_b32_e32 v111, v4
	v_mov_b32_e32 v112, v4
	v_mov_b32_e32 v113, v4
	v_mov_b32_e32 v114, v4
	v_mov_b32_e32 v115, v4
	v_mov_b32_e32 v116, v4
	v_mov_b32_e32 v117, v4
	v_mov_b32_e32 v118, v4
	v_mov_b32_e32 v119, v4
	v_mov_b32_e32 v120, v4
	v_mov_b32_e32 v121, v4
	v_mov_b32_e32 v122, v4
	v_mov_b32_e32 v123, v4
	v_mov_b32_e32 v124, v4
	v_mov_b32_e32 v125, v4
	v_mov_b32_e32 v126, v4
	v_mov_b32_e32 v127, v4
	v_mov_b32_e32 v128, v4
	v_mov_b32_e32 v129, v4
	v_mov_b32_e32 v130, v4
	v_mov_b32_e32 v131, v4
	s_mov_b64 s[30:31], 0xc000100
	s_mov_b64 s[56:57], 0xc040100
	s_mov_b64 s[58:59], 0xc000180
	s_mov_b64 s[60:61], 0xc040180
	s_waitcnt vmcnt(6)
	s_barrier

; #define WAIT_V8(n) asm volatile("s_waitcnt vmcnt(" #n ")" ::: "memory")
; #define BAR8 __builtin_amdgcn_s_barrier()
;     ...
;   const int brow = m0, bcol = n0;
;   const int wid = t >> 6, lane = t & 63, wr = wid >> 2, wc = wid & 3, fr = lane & 15, fq = lane >> 4;
;   f32x4 acc[2][2][4][2];
;   {
;     float zinit = 0.f;
;     asm volatile("" : "+v"(zinit));
; #pragma unroll
;     for (int a = 0; a < 2; ++a)
; #pragma unroll
;       for (int b = 0; b < 2; ++b)
; #pragma unroll
;         for (int m = 0; m < 4; ++m)
; #pragma unroll
;           for (int n = 0; n < 2; ++n)
; #pragma unroll
;             for (int j = 0; j < 4; ++j) acc[a][b][m][n][j] = zinit;
;   }
;   bf16x8 At[4][2], B0[2][2], B1[2][2];
;   const int nt = K / 64;
;   if (!pre) {
;     STAGE8(SB8(0, 0), Bt, K, bcol, 0); STAGE8(SA8(0, 0), A, lda, brow, 0);
;     STAGE8(SB8(0, 1), Bt, K, bcol + 128, 0); STAGE8(SA8(0, 1), A, lda, brow + 128, 0);
;   }
;   if (wr == 1) BAR8;
;   WAIT_V8(4); BAR8;
;   STAGE8(SB8(1, 0), Bt, K, bcol, 1); STAGE8(SA8(1, 0), A, lda, brow, 1); STAGE8(SB8(1, 1), Bt, K, bcol + 128, 1);
;   WAIT_V8(6); BAR8;
.LBB0_907:
	s_or_b64 exec, exec, s[12:13]
	s_lshl_b32 s29, s20, 11
	s_waitcnt vmcnt(0)
	v_add_u32_e32 v164, 0x18000, v150
	s_and_b32 s36, s29, 0x1f80000
	s_mov_b64 s[38:39], 0x80
	v_readfirstlane_b32 s29, v164
	v_add_u32_e32 v165, 0x1a000, v150
	v_lshl_add_u64 v[14:15], v[14:15], 0, s[38:39]
	s_mov_b32 m0, s29
	v_readfirstlane_b32 s29, v165
	v_add_u32_e32 v166, 0x8000, v150
	s_waitcnt vmcnt(4)
	s_barrier
	global_load_lds_dwordx4 v[14:15], off
	v_lshl_add_u64 v[14:15], v[18:19], 0, s[38:39]
	s_mov_b32 m0, s29
	v_readfirstlane_b32 s29, v166
	v_add_u32_e32 v168, 0xa000, v150
	global_load_lds_dwordx4 v[14:15], off
	v_lshl_add_u64 v[14:15], v[20:21], 0, s[38:39]
	s_mov_b32 m0, s29
	v_readfirstlane_b32 s29, v168
	v_add_u32_e32 v169, 0x1c000, v150
	global_load_lds_dwordx4 v[14:15], off
	v_lshl_add_u64 v[14:15], v[22:23], 0, s[38:39]
	s_mov_b32 m0, s29
	v_readfirstlane_b32 s29, v169
	v_add_u32_e32 v170, 0x1e000, v150
	global_load_lds_dwordx4 v[14:15], off
	v_lshl_add_u64 v[14:15], v[26:27], 0, s[38:39]
	s_mov_b32 m0, s29
	v_readfirstlane_b32 s29, v170
	global_load_lds_dwordx4 v[14:15], off
	v_lshl_add_u64 v[14:15], v[28:29], 0, s[38:39]
	s_mov_b32 m0, s29
	v_and_b32_e32 v147, 15, v3
	global_load_lds_dwordx4 v[14:15], off
	v_bfe_u32 v148, v3, 4, 2
	v_lshlrev_b32_e32 v14, 4, v148
	v_lshlrev_b32_e32 v15, 6, v147
	v_lshlrev_b32_e32 v18, 2, v3
	v_lshlrev_b64 v[136:137], 10, v[16:17]
	v_or_b32_e32 v17, v14, v15
	v_and_b32_e32 v18, 32, v18
	s_mov_b32 s29, 0x10000
	s_and_b32 s12, s21, 0xffffff00
	v_bitop3_b32 v20, v17, s29, v18 bitop3:0xde
	s_mov_b32 s29, 0x14000
	s_ashr_i32 s13, s12, 31
	v_readlane_b32 s40, v254, 35
	v_bitop3_b32 v19, v14, v18, v15 bitop3:0x36
	v_bitop3_b32 v21, v17, s29, v18 bitop3:0xde
	s_mov_b32 s29, 0x18000
	v_lshlrev_b32_e32 v15, 6, v3
	s_lshl_b64 s[12:13], s[12:13], 11
	s_mov_b32 s37, s40
	v_bitop3_b32 v22, v17, s29, v18 bitop3:0xde
	s_mov_b32 s29, 0x1c000
	v_and_b32_e32 v15, 0x3c0, v15
	v_bitop3_b32 v17, v17, s29, v18 bitop3:0xde
	v_bitop3_b32 v18, v15, v18, v14 bitop3:0x36
	v_lshl_add_u64 v[14:15], s[12:13], 0, v[6:7]
	v_lshl_add_u64 v[6:7], s[36:37], 0, v[6:7]
	v_lshl_add_u64 v[14:15], v[14:15], 0, v[8:9]
	v_lshl_add_u64 v[6:7], v[6:7], 0, v[8:9]
	v_bfe_u32 v146, v3, 6, 2
	v_lshlrev_b32_e32 v149, 6, v5
	v_lshlrev_b32_e32 v5, 13, v5
	v_lshl_add_u64 v[138:139], s[4:5], 0, v[14:15]
	v_lshl_add_u64 v[14:15], s[12:13], 0, v[10:11]
	v_lshl_add_u64 v[142:143], s[2:3], 0, v[6:7]
	v_lshl_add_u64 v[6:7], s[36:37], 0, v[10:11]
	v_lshlrev_b64 v[134:135], 10, v[24:25]
	v_readlane_b32 s41, v254, 36
	v_readlane_b32 s42, v254, 37
	v_readlane_b32 s43, v254, 38
	v_lshlrev_b32_e32 v16, 12, v146
	v_or_b32_e32 v23, 0x800, v5
	v_or_b32_e32 v24, 0x1000, v5
	v_or_b32_e32 v25, 0x1800, v5
	v_lshl_add_u64 v[14:15], v[14:15], 0, v[12:13]
	v_lshl_add_u64 v[6:7], v[6:7], 0, v[12:13]
	v_lshl_add_u64 v[140:141], s[4:5], 0, v[14:15]
	v_lshl_add_u64 v[144:145], s[2:3], 0, v[6:7]
	s_mov_b32 s29, -2
	s_mov_b64 s[12:13], 0
	v_add_u32_e32 v171, v20, v16
	v_add_u32_e32 v156, v19, v5
	v_add_u32_e32 v155, v18, v23
	v_add_u32_e32 v154, v18, v24
	v_add_u32_e32 v153, v18, v25
	v_add_u32_e32 v167, v21, v16
	v_add_u32_e32 v160, v22, v16
	v_add_u32_e32 v158, v17, v16
	v_mov_b32_e32 v5, v4
	v_mov_b32_e32 v6, v4
	v_mov_b32_e32 v7, v4
	v_mov_b32_e32 v8, v4
	v_mov_b32_e32 v9, v4
	v_mov_b32_e32 v10, v4
	v_mov_b32_e32 v11, v4
	v_mov_b32_e32 v12, v4
	v_mov_b32_e32 v13, v4
	v_mov_b32_e32 v14, v4
	v_mov_b32_e32 v15, v4
	v_mov_b32_e32 v16, v4
	v_mov_b32_e32 v17, v4
	v_mov_b32_e32 v18, v4
	v_mov_b32_e32 v19, v4
	v_mov_b32_e32 v20, v4
	v_mov_b32_e32 v21, v4
	v_mov_b32_e32 v22, v4
	v_mov_b32_e32 v23, v4
	v_mov_b32_e32 v24, v4
	v_mov_b32_e32 v25, v4
	v_mov_b32_e32 v26, v4
	v_mov_b32_e32 v27, v4
	v_mov_b32_e32 v28, v4
	v_mov_b32_e32 v29, v4
	v_mov_b32_e32 v30, v4
	v_mov_b32_e32 v31, v4
	v_mov_b32_e32 v32, v4
	v_mov_b32_e32 v33, v4
	v_mov_b32_e32 v34, v4
	v_mov_b32_e32 v35, v4
	v_mov_b32_e32 v36, v4
	v_mov_b32_e32 v37, v4
	v_mov_b32_e32 v38, v4
	v_mov_b32_e32 v39, v4
	v_mov_b32_e32 v40, v4
	v_mov_b32_e32 v41, v4
	v_mov_b32_e32 v42, v4
	v_mov_b32_e32 v43, v4
	v_mov_b32_e32 v44, v4
	v_mov_b32_e32 v45, v4
	v_mov_b32_e32 v46, v4
	v_mov_b32_e32 v47, v4
	v_mov_b32_e32 v48, v4
	v_mov_b32_e32 v49, v4
	v_mov_b32_e32 v50, v4
	v_mov_b32_e32 v51, v4
	v_mov_b32_e32 v52, v4
	v_mov_b32_e32 v53, v4
	v_mov_b32_e32 v54, v4
	v_mov_b32_e32 v55, v4
	v_mov_b32_e32 v56, v4
	v_mov_b32_e32 v57, v4
	v_mov_b32_e32 v58, v4
	v_mov_b32_e32 v59, v4
	v_mov_b32_e32 v60, v4
	v_mov_b32_e32 v61, v4
	v_mov_b32_e32 v62, v4
	v_mov_b32_e32 v63, v4
	v_mov_b32_e32 v64, v4
	v_mov_b32_e32 v65, v4
	v_mov_b32_e32 v66, v4
	v_mov_b32_e32 v67, v4
	v_mov_b32_e32 v68, v4
	v_mov_b32_e32 v69, v4
	v_mov_b32_e32 v70, v4
	v_mov_b32_e32 v71, v4
	v_mov_b32_e32 v72, v4
	v_mov_b32_e32 v73, v4
	v_mov_b32_e32 v74, v4
	v_mov_b32_e32 v75, v4
	v_mov_b32_e32 v76, v4
	v_mov_b32_e32 v77, v4
	v_mov_b32_e32 v78, v4
	v_mov_b32_e32 v79, v4
	v_mov_b32_e32 v80, v4
	v_mov_b32_e32 v81, v4
	v_mov_b32_e32 v82, v4
	v_mov_b32_e32 v83, v4
	v_mov_b32_e32 v84, v4
	v_mov_b32_e32 v85, v4
	v_mov_b32_e32 v86, v4
	v_mov_b32_e32 v87, v4
	v_mov_b32_e32 v88, v4
	v_mov_b32_e32 v89, v4
	v_mov_b32_e32 v90, v4
	v_mov_b32_e32 v91, v4
	v_mov_b32_e32 v92, v4
	v_mov_b32_e32 v93, v4
	v_mov_b32_e32 v94, v4
	v_mov_b32_e32 v95, v4
	v_mov_b32_e32 v96, v4
	v_mov_b32_e32 v97, v4
	v_mov_b32_e32 v98, v4
	v_mov_b32_e32 v99, v4
	v_mov_b32_e32 v100, v4
	v_mov_b32_e32 v101, v4
	v_mov_b32_e32 v102, v4
	v_mov_b32_e32 v103, v4
	v_mov_b32_e32 v104, v4
	v_mov_b32_e32 v105, v4
	v_mov_b32_e32 v106, v4
	v_mov_b32_e32 v107, v4
	v_mov_b32_e32 v108, v4
	v_mov_b32_e32 v109, v4
	v_mov_b32_e32 v110, v4
	v_mov_b32_e32 v111, v4
	v_mov_b32_e32 v112, v4
	v_mov_b32_e32 v113, v4
	v_mov_b32_e32 v114, v4
	v_mov_b32_e32 v115, v4
	v_mov_b32_e32 v116, v4
	v_mov_b32_e32 v117, v4
	v_mov_b32_e32 v118, v4
	v_mov_b32_e32 v119, v4
	v_mov_b32_e32 v120, v4
	v_mov_b32_e32 v121, v4
	v_mov_b32_e32 v122, v4
	v_mov_b32_e32 v123, v4
	v_mov_b32_e32 v124, v4
	v_mov_b32_e32 v125, v4
	v_mov_b32_e32 v126, v4
	v_mov_b32_e32 v127, v4
	v_mov_b32_e32 v128, v4
	v_mov_b32_e32 v129, v4
	v_mov_b32_e32 v130, v4
	v_mov_b32_e32 v131, v4
	s_mov_b64 s[36:37], 0x6040080
	s_mov_b64 s[38:39], 0xc4a0100
	s_mov_b64 s[40:41], 0x6000100
	s_mov_b64 s[42:43], 0xc4e0100
	s_mov_b64 s[44:45], 0x6040100
	s_mov_b64 s[46:47], 0xc4a0180
	s_mov_b64 s[48:49], 0x6000180
	s_mov_b64 s[50:51], 0xc4e0180
	s_waitcnt vmcnt(6)
	s_barrier

; #define WAIT_V8(n) asm volatile("s_waitcnt vmcnt(" #n ")" ::: "memory")
; #define BAR8 __builtin_amdgcn_s_barrier()
;     ...
;   const int brow = m0, bcol = n0;
;   const int wid = t >> 6, lane = t & 63, wr = wid >> 2, wc = wid & 3, fr = lane & 15, fq = lane >> 4;
;   f32x4 acc[2][2][4][2];
;   {
;     float zinit = 0.f;
;     asm volatile("" : "+v"(zinit));
; #pragma unroll
;     for (int a = 0; a < 2; ++a)
; #pragma unroll
;       for (int b = 0; b < 2; ++b)
; #pragma unroll
;         for (int m = 0; m < 4; ++m)
; #pragma unroll
;           for (int n = 0; n < 2; ++n)
; #pragma unroll
;             for (int j = 0; j < 4; ++j) acc[a][b][m][n][j] = zinit;
;   }
;   bf16x8 At[4][2], B0[2][2], B1[2][2];
;   const int nt = K / 64;
;   if (!pre) {
;     STAGE8(SB8(0, 0), Bt, K, bcol, 0); STAGE8(SA8(0, 0), A, lda, brow, 0);
;     STAGE8(SB8(0, 1), Bt, K, bcol + 128, 0); STAGE8(SA8(0, 1), A, lda, brow + 128, 0);
;   }
;   if (wr == 1) BAR8;
;   WAIT_V8(4); BAR8;
;   STAGE8(SB8(1, 0), Bt, K, bcol, 1); STAGE8(SA8(1, 0), A, lda, brow, 1); STAGE8(SB8(1, 1), Bt, K, bcol + 128, 1);
;   WAIT_V8(6); BAR8;
.LBB0_1004:
	s_or_b64 exec, exec, s[20:21]
	v_readlane_b32 s40, v254, 35
	s_lshl_b32 s20, s36, 10
	v_readlane_b32 s42, v254, 37
	v_readlane_b32 s43, v254, 38
	s_waitcnt vmcnt(0)
	v_add_u32_e32 v164, 0x18000, v150
	s_and_b32 s20, s20, 0xfffc0000
	s_mov_b32 s21, s40
	s_mov_b64 s[42:43], 0x80
	v_readfirstlane_b32 s40, v164
	v_add_u32_e32 v165, 0x1a000, v150
	s_and_b32 s1, s27, 7
	s_add_i32 s20, s20, 0xffc00000
	v_lshl_add_u64 v[10:11], v[10:11], 0, s[42:43]
	s_mov_b32 m0, s40
	v_readfirstlane_b32 s40, v165
	v_add_u32_e32 v166, 0x8000, v150
	s_lshl_b32 s1, s1, 19
	s_lshl_b64 s[20:21], s[20:21], 1
	s_waitcnt vmcnt(4)
	s_barrier
	global_load_lds_dwordx4 v[10:11], off
	v_lshl_add_u64 v[10:11], v[12:13], 0, s[42:43]
	s_mov_b32 m0, s40
	v_readfirstlane_b32 s40, v166
	v_add_u32_e32 v167, 0xa000, v150
	global_load_lds_dwordx4 v[10:11], off
	v_lshl_add_u64 v[10:11], v[16:17], 0, s[42:43]
	s_mov_b32 m0, s40
	v_readfirstlane_b32 s40, v167
	s_add_u32 s14, s14, 0x40080
	global_load_lds_dwordx4 v[10:11], off
	v_lshl_add_u64 v[10:11], v[14:15], 0, s[42:43]
	s_mov_b32 m0, s40
	s_addc_u32 s15, s15, 0
	v_add_u32_e32 v169, 0x1c000, v150
	global_load_lds_dwordx4 v[10:11], off
	v_lshl_add_u64 v[10:11], s[14:15], 0, v[132:133]
	v_readfirstlane_b32 s40, v169
	v_lshl_add_u64 v[10:11], v[10:11], 0, v[6:7]
	s_mov_b32 m0, s40
	v_add_u32_e32 v170, 0x1e000, v150
	global_load_lds_dwordx4 v[10:11], off
	v_lshl_add_u64 v[10:11], s[14:15], 0, v[136:137]
	v_readfirstlane_b32 s14, v170
	v_lshl_add_u64 v[10:11], v[10:11], 0, v[8:9]
	s_mov_b32 m0, s14
	v_and_b32_e32 v147, 15, v3
	global_load_lds_dwordx4 v[10:11], off
	v_bfe_u32 v148, v3, 4, 2
	v_lshlrev_b32_e32 v11, 4, v148
	v_lshlrev_b32_e32 v12, 6, v147
	v_lshlrev_b32_e32 v14, 2, v3
	v_or_b32_e32 v13, v11, v12
	v_and_b32_e32 v14, 32, v14
	s_mov_b32 s14, 0x10000
	v_bitop3_b32 v15, v13, s14, v14 bitop3:0xde
	s_mov_b32 s14, 0x14000
	s_add_u32 s12, s12, s1
	v_bitop3_b32 v16, v13, s14, v14 bitop3:0xde
	s_mov_b32 s14, 0x18000
	v_lshlrev_b32_e32 v18, 6, v3
	s_addc_u32 s13, s13, 0
	v_lshl_add_u64 v[8:9], v[136:137], 0, v[8:9]
	v_lshl_add_u64 v[6:7], v[132:133], 0, v[6:7]
	v_bfe_u32 v146, v3, 6, 2
	v_lshlrev_b32_e32 v149, 6, v5
	v_bitop3_b32 v17, v13, s14, v14 bitop3:0xde
	s_mov_b32 s14, 0x1c000
	v_lshlrev_b32_e32 v5, 13, v5
	v_and_b32_e32 v18, 0x3c0, v18
	v_lshl_add_u64 v[138:139], s[12:13], 0, v[8:9]
	v_lshl_add_u64 v[140:141], s[12:13], 0, v[6:7]
	s_add_u32 s12, s4, s20
	v_readlane_b32 s41, v254, 36
	v_lshlrev_b32_e32 v10, 12, v146
	v_bitop3_b32 v12, v11, v14, v12 bitop3:0x36
	v_bitop3_b32 v13, v13, s14, v14 bitop3:0xde
	v_bitop3_b32 v11, v18, v14, v11 bitop3:0x36
	v_or_b32_e32 v14, 0x800, v5
	v_or_b32_e32 v18, 0x1000, v5
	v_or_b32_e32 v19, 0x1800, v5
	s_addc_u32 s13, s5, s21
	v_lshl_add_u64 v[142:143], s[12:13], 0, v[6:7]
	v_lshl_add_u64 v[144:145], s[12:13], 0, v[8:9]
	s_mov_b32 s1, -2
	s_mov_b64 s[12:13], 0
	v_add_u32_e32 v171, v15, v10
	v_add_u32_e32 v156, v12, v5
	v_add_u32_e32 v155, v11, v14
	v_add_u32_e32 v154, v11, v18
	v_add_u32_e32 v153, v11, v19
	v_add_u32_e32 v168, v16, v10
	v_add_u32_e32 v161, v17, v10
	v_add_u32_e32 v158, v13, v10
	v_mov_b32_e32 v5, v4
	v_mov_b32_e32 v6, v4
	v_mov_b32_e32 v7, v4
	v_mov_b32_e32 v8, v4
	v_mov_b32_e32 v9, v4
	v_mov_b32_e32 v10, v4
	v_mov_b32_e32 v11, v4
	v_mov_b32_e32 v12, v4
	v_mov_b32_e32 v13, v4
	v_mov_b32_e32 v14, v4
	v_mov_b32_e32 v15, v4
	v_mov_b32_e32 v16, v4
	v_mov_b32_e32 v17, v4
	v_mov_b32_e32 v18, v4
	v_mov_b32_e32 v19, v4
	v_mov_b32_e32 v20, v4
	v_mov_b32_e32 v21, v4
	v_mov_b32_e32 v22, v4
	v_mov_b32_e32 v23, v4
	v_mov_b32_e32 v24, v4
	v_mov_b32_e32 v25, v4
	v_mov_b32_e32 v26, v4
	v_mov_b32_e32 v27, v4
	v_mov_b32_e32 v28, v4
	v_mov_b32_e32 v29, v4
	v_mov_b32_e32 v30, v4
	v_mov_b32_e32 v31, v4
	v_mov_b32_e32 v32, v4
	v_mov_b32_e32 v33, v4
	v_mov_b32_e32 v34, v4
	v_mov_b32_e32 v35, v4
	v_mov_b32_e32 v36, v4
	v_mov_b32_e32 v37, v4
	v_mov_b32_e32 v38, v4
	v_mov_b32_e32 v39, v4
	v_mov_b32_e32 v40, v4
	v_mov_b32_e32 v41, v4
	v_mov_b32_e32 v42, v4
	v_mov_b32_e32 v43, v4
	v_mov_b32_e32 v44, v4
	v_mov_b32_e32 v45, v4
	v_mov_b32_e32 v46, v4
	v_mov_b32_e32 v47, v4
	v_mov_b32_e32 v48, v4
	v_mov_b32_e32 v49, v4
	v_mov_b32_e32 v50, v4
	v_mov_b32_e32 v51, v4
	v_mov_b32_e32 v52, v4
	v_mov_b32_e32 v53, v4
	v_mov_b32_e32 v54, v4
	v_mov_b32_e32 v55, v4
	v_mov_b32_e32 v56, v4
	v_mov_b32_e32 v57, v4
	v_mov_b32_e32 v58, v4
	v_mov_b32_e32 v59, v4
	v_mov_b32_e32 v60, v4
	v_mov_b32_e32 v61, v4
	v_mov_b32_e32 v62, v4
	v_mov_b32_e32 v63, v4
	v_mov_b32_e32 v64, v4
	v_mov_b32_e32 v65, v4
	v_mov_b32_e32 v66, v4
	v_mov_b32_e32 v67, v4
	v_mov_b32_e32 v68, v4
	v_mov_b32_e32 v69, v4
	v_mov_b32_e32 v70, v4
	v_mov_b32_e32 v71, v4
	v_mov_b32_e32 v72, v4
	v_mov_b32_e32 v73, v4
	v_mov_b32_e32 v74, v4
	v_mov_b32_e32 v75, v4
	v_mov_b32_e32 v76, v4
	v_mov_b32_e32 v77, v4
	v_mov_b32_e32 v78, v4
	v_mov_b32_e32 v79, v4
	v_mov_b32_e32 v80, v4
	v_mov_b32_e32 v81, v4
	v_mov_b32_e32 v82, v4
	v_mov_b32_e32 v83, v4
	v_mov_b32_e32 v84, v4
	v_mov_b32_e32 v85, v4
	v_mov_b32_e32 v86, v4
	v_mov_b32_e32 v87, v4
	v_mov_b32_e32 v88, v4
	v_mov_b32_e32 v89, v4
	v_mov_b32_e32 v90, v4
	v_mov_b32_e32 v91, v4
	v_mov_b32_e32 v92, v4
	v_mov_b32_e32 v93, v4
	v_mov_b32_e32 v94, v4
	v_mov_b32_e32 v95, v4
	v_mov_b32_e32 v96, v4
	v_mov_b32_e32 v97, v4
	v_mov_b32_e32 v98, v4
	v_mov_b32_e32 v99, v4
	v_mov_b32_e32 v100, v4
	v_mov_b32_e32 v101, v4
	v_mov_b32_e32 v102, v4
	v_mov_b32_e32 v103, v4
	v_mov_b32_e32 v104, v4
	v_mov_b32_e32 v105, v4
	v_mov_b32_e32 v106, v4
	v_mov_b32_e32 v107, v4
	v_mov_b32_e32 v108, v4
	v_mov_b32_e32 v109, v4
	v_mov_b32_e32 v110, v4
	v_mov_b32_e32 v111, v4
	v_mov_b32_e32 v112, v4
	v_mov_b32_e32 v113, v4
	v_mov_b32_e32 v114, v4
	v_mov_b32_e32 v115, v4
	v_mov_b32_e32 v116, v4
	v_mov_b32_e32 v117, v4
	v_mov_b32_e32 v118, v4
	v_mov_b32_e32 v119, v4
	v_mov_b32_e32 v120, v4
	v_mov_b32_e32 v121, v4
	v_mov_b32_e32 v122, v4
	v_mov_b32_e32 v123, v4
	v_mov_b32_e32 v124, v4
	v_mov_b32_e32 v125, v4
	v_mov_b32_e32 v126, v4
	v_mov_b32_e32 v127, v4
	v_mov_b32_e32 v128, v4
	v_mov_b32_e32 v129, v4
	v_mov_b32_e32 v130, v4
	v_mov_b32_e32 v131, v4
	s_mov_b64 s[20:21], 0xb840080
	s_mov_b64 s[40:41], 0xc7a0100
	s_mov_b64 s[42:43], 0xb800100
	s_mov_b64 s[44:45], 0xc7e0100
	s_mov_b64 s[46:47], 0xb840100
	s_mov_b64 s[48:49], 0xc7a0180
	s_mov_b64 s[50:51], 0xb800180
	s_mov_b64 s[52:53], 0xc7e0180
	s_waitcnt vmcnt(6)
	s_barrier

; #define WAIT_V8(n) asm volatile("s_waitcnt vmcnt(" #n ")" ::: "memory")
; #define BAR8 __builtin_amdgcn_s_barrier()
;     ...
;   const int brow = m0, bcol = n0;
;   const int wid = t >> 6, lane = t & 63, wr = wid >> 2, wc = wid & 3, fr = lane & 15, fq = lane >> 4;
;   f32x4 acc[2][2][4][2];
;   {
;     float zinit = 0.f;
;     asm volatile("" : "+v"(zinit));
; #pragma unroll
;     for (int a = 0; a < 2; ++a)
; #pragma unroll
;       for (int b = 0; b < 2; ++b)
; #pragma unroll
;         for (int m = 0; m < 4; ++m)
; #pragma unroll
;           for (int n = 0; n < 2; ++n)
; #pragma unroll
;             for (int j = 0; j < 4; ++j) acc[a][b][m][n][j] = zinit;
;   }
;   bf16x8 At[4][2], B0[2][2], B1[2][2];
;   const int nt = K / 64;
;   if (!pre) {
;     STAGE8(SB8(0, 0), Bt, K, bcol, 0); STAGE8(SA8(0, 0), A, lda, brow, 0);
;     STAGE8(SB8(0, 1), Bt, K, bcol + 128, 0); STAGE8(SA8(0, 1), A, lda, brow + 128, 0);
;   }
;   if (wr == 1) BAR8;
;   WAIT_V8(4); BAR8;
;   STAGE8(SB8(1, 0), Bt, K, bcol, 1); STAGE8(SA8(1, 0), A, lda, brow, 1); STAGE8(SB8(1, 1), Bt, K, bcol + 128, 1);
;   WAIT_V8(6); BAR8;
.LBB0_1014:
	s_or_b64 exec, exec, s[14:15]
	v_readlane_b32 s40, v254, 35
	v_readlane_b32 s42, v254, 37
	v_readlane_b32 s43, v254, 38
	s_waitcnt vmcnt(0)
	v_add_u32_e32 v164, 0x18000, v150
	s_mov_b64 s[42:43], 0x80
	v_readfirstlane_b32 s21, v164
	v_add_u32_e32 v165, 0x1a000, v150
	v_lshl_add_u64 v[10:11], v[10:11], 0, s[42:43]
	s_mov_b32 m0, s21
	v_readfirstlane_b32 s21, v165
	v_add_u32_e32 v166, 0x8000, v150
	s_waitcnt vmcnt(4)
	s_barrier
	global_load_lds_dwordx4 v[10:11], off
	v_lshl_add_u64 v[10:11], v[12:13], 0, s[42:43]
	s_mov_b32 m0, s21
	v_readfirstlane_b32 s21, v166
	v_add_u32_e32 v167, 0xa000, v150
	global_load_lds_dwordx4 v[10:11], off
	v_lshl_add_u64 v[10:11], v[14:15], 0, s[42:43]
	s_mov_b32 m0, s21
	v_readfirstlane_b32 s21, v167
	v_add_u32_e32 v169, 0x1c000, v150
	global_load_lds_dwordx4 v[10:11], off
	v_lshl_add_u64 v[10:11], v[16:17], 0, s[42:43]
	s_mov_b32 m0, s21
	v_readfirstlane_b32 s21, v169
	v_add_u32_e32 v170, 0x1e000, v150
	global_load_lds_dwordx4 v[10:11], off
	v_lshl_add_u64 v[10:11], v[18:19], 0, s[42:43]
	s_mov_b32 m0, s21
	v_readfirstlane_b32 s21, v170
	global_load_lds_dwordx4 v[10:11], off
	v_lshl_add_u64 v[10:11], v[20:21], 0, s[42:43]
	s_mov_b32 m0, s21
	v_and_b32_e32 v147, 15, v3
	global_load_lds_dwordx4 v[10:11], off
	v_bfe_u32 v148, v3, 4, 2
	v_lshlrev_b32_e32 v10, 4, v148
	v_lshlrev_b32_e32 v11, 6, v147
	v_lshlrev_b32_e32 v14, 2, v3
	v_or_b32_e32 v13, v10, v11
	v_and_b32_e32 v14, 32, v14
	s_mov_b32 s21, 0x10000
	v_bitop3_b32 v16, v13, s21, v14 bitop3:0xde
	s_mov_b32 s21, 0x14000
	s_and_b32 s14, s27, 63
	v_bitop3_b32 v15, v10, v14, v11 bitop3:0x36
	v_bitop3_b32 v17, v13, s21, v14 bitop3:0xde
	s_mov_b32 s21, 0x18000
	v_lshlrev_b32_e32 v11, 6, v3
	s_lshl_b32 s14, s14, 19
	s_mov_b32 s15, s40
	v_bitop3_b32 v18, v13, s21, v14 bitop3:0xde
	s_mov_b32 s21, 0x1c000
	v_and_b32_e32 v11, 0x3c0, v11
	v_bitop3_b32 v13, v13, s21, v14 bitop3:0xde
	v_bitop3_b32 v14, v11, v14, v10 bitop3:0x36
	v_lshl_add_u64 v[10:11], s[14:15], 0, v[136:137]
	v_readlane_b32 s41, v254, 36
	s_and_b32 s40, s33, 0xffffff00
	v_lshl_add_u64 v[10:11], v[10:11], 0, v[8:9]
	s_ashr_i32 s41, s40, 31
	v_lshl_add_u64 v[138:139], s[12:13], 0, v[10:11]
	v_lshl_add_u64 v[10:11], s[14:15], 0, v[132:133]
	s_lshl_b64 s[40:41], s[40:41], 11
	v_lshl_add_u64 v[10:11], v[10:11], 0, v[6:7]
	v_lshl_add_u64 v[140:141], s[12:13], 0, v[10:11]
	v_lshl_add_u64 v[10:11], s[40:41], 0, v[132:133]
	v_lshl_add_u64 v[6:7], v[10:11], 0, v[6:7]
	v_bfe_u32 v146, v3, 6, 2
	v_lshlrev_b32_e32 v149, 6, v5
	v_lshlrev_b32_e32 v5, 13, v5
	v_lshl_add_u64 v[142:143], s[4:5], 0, v[6:7]
	v_lshl_add_u64 v[6:7], s[40:41], 0, v[136:137]
	v_lshlrev_b32_e32 v12, 12, v146
	v_or_b32_e32 v19, 0x800, v5
	v_or_b32_e32 v20, 0x1000, v5
	v_or_b32_e32 v21, 0x1800, v5
	v_lshl_add_u64 v[6:7], v[6:7], 0, v[8:9]
	v_lshl_add_u64 v[144:145], s[4:5], 0, v[6:7]
	s_mov_b32 s14, -2
	s_mov_b64 s[12:13], 0
	v_add_u32_e32 v171, v16, v12
	v_add_u32_e32 v156, v15, v5
	v_add_u32_e32 v155, v14, v19
	v_add_u32_e32 v154, v14, v20
	v_add_u32_e32 v153, v14, v21
	v_add_u32_e32 v168, v17, v12
	v_add_u32_e32 v161, v18, v12
	v_add_u32_e32 v158, v13, v12
	v_mov_b32_e32 v5, v4
	v_mov_b32_e32 v6, v4
	v_mov_b32_e32 v7, v4
	v_mov_b32_e32 v8, v4
	v_mov_b32_e32 v9, v4
	v_mov_b32_e32 v10, v4
	v_mov_b32_e32 v11, v4
	v_mov_b32_e32 v12, v4
	v_mov_b32_e32 v13, v4
	v_mov_b32_e32 v14, v4
	v_mov_b32_e32 v15, v4
	v_mov_b32_e32 v16, v4
	v_mov_b32_e32 v17, v4
	v_mov_b32_e32 v18, v4
	v_mov_b32_e32 v19, v4
	v_mov_b32_e32 v20, v4
	v_mov_b32_e32 v21, v4
	v_mov_b32_e32 v22, v4
	v_mov_b32_e32 v23, v4
	v_mov_b32_e32 v24, v4
	v_mov_b32_e32 v25, v4
	v_mov_b32_e32 v26, v4
	v_mov_b32_e32 v27, v4
	v_mov_b32_e32 v28, v4
	v_mov_b32_e32 v29, v4
	v_mov_b32_e32 v30, v4
	v_mov_b32_e32 v31, v4
	v_mov_b32_e32 v32, v4
	v_mov_b32_e32 v33, v4
	v_mov_b32_e32 v34, v4
	v_mov_b32_e32 v35, v4
	v_mov_b32_e32 v36, v4
	v_mov_b32_e32 v37, v4
	v_mov_b32_e32 v38, v4
	v_mov_b32_e32 v39, v4
	v_mov_b32_e32 v40, v4
	v_mov_b32_e32 v41, v4
	v_mov_b32_e32 v42, v4
	v_mov_b32_e32 v43, v4
	v_mov_b32_e32 v44, v4
	v_mov_b32_e32 v45, v4
	v_mov_b32_e32 v46, v4
	v_mov_b32_e32 v47, v4
	v_mov_b32_e32 v48, v4
	v_mov_b32_e32 v49, v4
	v_mov_b32_e32 v50, v4
	v_mov_b32_e32 v51, v4
	v_mov_b32_e32 v52, v4
	v_mov_b32_e32 v53, v4
	v_mov_b32_e32 v54, v4
	v_mov_b32_e32 v55, v4
	v_mov_b32_e32 v56, v4
	v_mov_b32_e32 v57, v4
	v_mov_b32_e32 v58, v4
	v_mov_b32_e32 v59, v4
	v_mov_b32_e32 v60, v4
	v_mov_b32_e32 v61, v4
	v_mov_b32_e32 v62, v4
	v_mov_b32_e32 v63, v4
	v_mov_b32_e32 v64, v4
	v_mov_b32_e32 v65, v4
	v_mov_b32_e32 v66, v4
	v_mov_b32_e32 v67, v4
	v_mov_b32_e32 v68, v4
	v_mov_b32_e32 v69, v4
	v_mov_b32_e32 v70, v4
	v_mov_b32_e32 v71, v4
	v_mov_b32_e32 v72, v4
	v_mov_b32_e32 v73, v4
	v_mov_b32_e32 v74, v4
	v_mov_b32_e32 v75, v4
	v_mov_b32_e32 v76, v4
	v_mov_b32_e32 v77, v4
	v_mov_b32_e32 v78, v4
	v_mov_b32_e32 v79, v4
	v_mov_b32_e32 v80, v4
	v_mov_b32_e32 v81, v4
	v_mov_b32_e32 v82, v4
	v_mov_b32_e32 v83, v4
	v_mov_b32_e32 v84, v4
	v_mov_b32_e32 v85, v4
	v_mov_b32_e32 v86, v4
	v_mov_b32_e32 v87, v4
	v_mov_b32_e32 v88, v4
	v_mov_b32_e32 v89, v4
	v_mov_b32_e32 v90, v4
	v_mov_b32_e32 v91, v4
	v_mov_b32_e32 v92, v4
	v_mov_b32_e32 v93, v4
	v_mov_b32_e32 v94, v4
	v_mov_b32_e32 v95, v4
	v_mov_b32_e32 v96, v4
	v_mov_b32_e32 v97, v4
	v_mov_b32_e32 v98, v4
	v_mov_b32_e32 v99, v4
	v_mov_b32_e32 v100, v4
	v_mov_b32_e32 v101, v4
	v_mov_b32_e32 v102, v4
	v_mov_b32_e32 v103, v4
	v_mov_b32_e32 v104, v4
	v_mov_b32_e32 v105, v4
	v_mov_b32_e32 v106, v4
	v_mov_b32_e32 v107, v4
	v_mov_b32_e32 v108, v4
	v_mov_b32_e32 v109, v4
	v_mov_b32_e32 v110, v4
	v_mov_b32_e32 v111, v4
	v_mov_b32_e32 v112, v4
	v_mov_b32_e32 v113, v4
	v_mov_b32_e32 v114, v4
	v_mov_b32_e32 v115, v4
	v_mov_b32_e32 v116, v4
	v_mov_b32_e32 v117, v4
	v_mov_b32_e32 v118, v4
	v_mov_b32_e32 v119, v4
	v_mov_b32_e32 v120, v4
	v_mov_b32_e32 v121, v4
	v_mov_b32_e32 v122, v4
	v_mov_b32_e32 v123, v4
	v_mov_b32_e32 v124, v4
	v_mov_b32_e32 v125, v4
	v_mov_b32_e32 v126, v4
	v_mov_b32_e32 v127, v4
	v_mov_b32_e32 v128, v4
	v_mov_b32_e32 v129, v4
	v_mov_b32_e32 v130, v4
	v_mov_b32_e32 v131, v4
	s_mov_b64 s[40:41], 0xc6a0100
	s_mov_b64 s[42:43], 0xc6e0100
	s_mov_b64 s[44:45], 0xc6a0180
	s_mov_b64 s[46:47], 0xc6e0180
	s_waitcnt vmcnt(6)
	s_barrier

; #define WAIT_V8(n) asm volatile("s_waitcnt vmcnt(" #n ")" ::: "memory")
; #define BAR8 __builtin_amdgcn_s_barrier()
;     ...
;   const int brow = m0, bcol = n0;
;   const int wid = t >> 6, lane = t & 63, wr = wid >> 2, wc = wid & 3, fr = lane & 15, fq = lane >> 4;
;   f32x4 acc[2][2][4][2];
;   {
;     float zinit = 0.f;
;     asm volatile("" : "+v"(zinit));
; #pragma unroll
;     for (int a = 0; a < 2; ++a)
; #pragma unroll
;       for (int b = 0; b < 2; ++b)
; #pragma unroll
;         for (int m = 0; m < 4; ++m)
; #pragma unroll
;           for (int n = 0; n < 2; ++n)
; #pragma unroll
;             for (int j = 0; j < 4; ++j) acc[a][b][m][n][j] = zinit;
;   }
;   bf16x8 At[4][2], B0[2][2], B1[2][2];
;   const int nt = K / 64;
;   if (!pre) {
;     STAGE8(SB8(0, 0), Bt, K, bcol, 0); STAGE8(SA8(0, 0), A, lda, brow, 0);
;     STAGE8(SB8(0, 1), Bt, K, bcol + 128, 0); STAGE8(SA8(0, 1), A, lda, brow + 128, 0);
;   }
;   if (wr == 1) BAR8;
;   WAIT_V8(4); BAR8;
;   STAGE8(SB8(1, 0), Bt, K, bcol, 1); STAGE8(SA8(1, 0), A, lda, brow, 1); STAGE8(SB8(1, 1), Bt, K, bcol + 128, 1);
;   WAIT_V8(6); BAR8;
.LBB0_1151:
	s_or_b64 exec, exec, s[12:13]
	s_lshl_b32 s29, s20, 10
	v_add_u32_e32 v164, 0x18000, v150
	s_and_b32 s36, s29, 0xfc0000
	s_mov_b64 s[38:39], 0x80
	v_readfirstlane_b32 s29, v164
	v_add_u32_e32 v165, 0x1a000, v150
	v_lshl_add_u64 v[14:15], v[14:15], 0, s[38:39]
	s_mov_b32 m0, s29
	v_readfirstlane_b32 s29, v165
	v_add_u32_e32 v166, 0x8000, v150
	s_waitcnt vmcnt(4)
	s_barrier
	global_load_lds_dwordx4 v[14:15], off
	v_lshl_add_u64 v[14:15], v[18:19], 0, s[38:39]
	s_mov_b32 m0, s29
	v_readfirstlane_b32 s29, v166
	v_add_u32_e32 v168, 0xa000, v150
	global_load_lds_dwordx4 v[14:15], off
	v_lshl_add_u64 v[14:15], v[20:21], 0, s[38:39]
	s_mov_b32 m0, s29
	v_readfirstlane_b32 s29, v168
	v_add_u32_e32 v169, 0x1c000, v150
	global_load_lds_dwordx4 v[14:15], off
	v_lshl_add_u64 v[14:15], v[22:23], 0, s[38:39]
	s_mov_b32 m0, s29
	v_readfirstlane_b32 s29, v169
	v_add_u32_e32 v170, 0x1e000, v150
	global_load_lds_dwordx4 v[14:15], off
	v_lshl_add_u64 v[14:15], v[26:27], 0, s[38:39]
	s_mov_b32 m0, s29
	v_readfirstlane_b32 s29, v170
	global_load_lds_dwordx4 v[14:15], off
	v_lshl_add_u64 v[14:15], v[28:29], 0, s[38:39]
	s_mov_b32 m0, s29
	v_and_b32_e32 v147, 15, v3
	global_load_lds_dwordx4 v[14:15], off
	v_bfe_u32 v148, v3, 4, 2
	v_lshlrev_b32_e32 v14, 4, v148
	v_lshlrev_b32_e32 v15, 6, v147
	v_lshlrev_b32_e32 v18, 2, v3
	v_lshlrev_b64 v[136:137], 9, v[16:17]
	v_or_b32_e32 v17, v14, v15
	v_and_b32_e32 v18, 32, v18
	s_mov_b32 s29, 0x10000
	s_and_b32 s12, s21, 0xffffff00
	v_bitop3_b32 v20, v17, s29, v18 bitop3:0xde
	s_mov_b32 s29, 0x14000
	s_ashr_i32 s13, s12, 31
	v_readlane_b32 s40, v254, 35
	v_bitop3_b32 v19, v14, v18, v15 bitop3:0x36
	v_bitop3_b32 v21, v17, s29, v18 bitop3:0xde
	s_mov_b32 s29, 0x18000
	v_lshlrev_b32_e32 v15, 6, v3
	s_lshl_b64 s[12:13], s[12:13], 10
	s_mov_b32 s37, s40
	v_bitop3_b32 v22, v17, s29, v18 bitop3:0xde
	s_mov_b32 s29, 0x1c000
	v_and_b32_e32 v15, 0x3c0, v15
	v_bitop3_b32 v17, v17, s29, v18 bitop3:0xde
	v_bitop3_b32 v18, v15, v18, v14 bitop3:0x36
	v_lshl_add_u64 v[14:15], s[12:13], 0, v[6:7]
	v_lshl_add_u64 v[6:7], s[36:37], 0, v[6:7]
	v_lshl_add_u64 v[14:15], v[14:15], 0, v[8:9]
	v_lshl_add_u64 v[6:7], v[6:7], 0, v[8:9]
	v_bfe_u32 v146, v3, 6, 2
	v_lshlrev_b32_e32 v149, 6, v5
	v_lshlrev_b32_e32 v5, 13, v5
	v_lshl_add_u64 v[138:139], s[4:5], 0, v[14:15]
	v_lshl_add_u64 v[14:15], s[12:13], 0, v[10:11]
	v_lshl_add_u64 v[142:143], s[2:3], 0, v[6:7]
	v_lshl_add_u64 v[6:7], s[36:37], 0, v[10:11]
	v_lshlrev_b64 v[134:135], 9, v[24:25]
	v_readlane_b32 s41, v254, 36
	v_readlane_b32 s42, v254, 37
	v_readlane_b32 s43, v254, 38
	v_lshlrev_b32_e32 v16, 12, v146
	v_or_b32_e32 v23, 0x800, v5
	v_or_b32_e32 v24, 0x1000, v5
	v_or_b32_e32 v25, 0x1800, v5
	v_lshl_add_u64 v[14:15], v[14:15], 0, v[12:13]
	v_lshl_add_u64 v[6:7], v[6:7], 0, v[12:13]
	v_lshl_add_u64 v[140:141], s[4:5], 0, v[14:15]
	v_lshl_add_u64 v[144:145], s[2:3], 0, v[6:7]
	s_mov_b32 s29, -2
	s_mov_b64 s[12:13], 0
	v_add_u32_e32 v171, v20, v16
	v_add_u32_e32 v156, v19, v5
	v_add_u32_e32 v155, v18, v23
	v_add_u32_e32 v154, v18, v24
	v_add_u32_e32 v153, v18, v25
	v_add_u32_e32 v167, v21, v16
	v_add_u32_e32 v160, v22, v16
	v_add_u32_e32 v158, v17, v16
	v_mov_b32_e32 v5, v4
	v_mov_b32_e32 v6, v4
	v_mov_b32_e32 v7, v4
	v_mov_b32_e32 v8, v4
	v_mov_b32_e32 v9, v4
	v_mov_b32_e32 v10, v4
	v_mov_b32_e32 v11, v4
	v_mov_b32_e32 v12, v4
	v_mov_b32_e32 v13, v4
	v_mov_b32_e32 v14, v4
	v_mov_b32_e32 v15, v4
	v_mov_b32_e32 v16, v4
	v_mov_b32_e32 v17, v4
	v_mov_b32_e32 v18, v4
	v_mov_b32_e32 v19, v4
	v_mov_b32_e32 v20, v4
	v_mov_b32_e32 v21, v4
	v_mov_b32_e32 v22, v4
	v_mov_b32_e32 v23, v4
	v_mov_b32_e32 v24, v4
	v_mov_b32_e32 v25, v4
	v_mov_b32_e32 v26, v4
	v_mov_b32_e32 v27, v4
	v_mov_b32_e32 v28, v4
	v_mov_b32_e32 v29, v4
	v_mov_b32_e32 v30, v4
	v_mov_b32_e32 v31, v4
	v_mov_b32_e32 v32, v4
	v_mov_b32_e32 v33, v4
	v_mov_b32_e32 v34, v4
	v_mov_b32_e32 v35, v4
	v_mov_b32_e32 v36, v4
	v_mov_b32_e32 v37, v4
	v_mov_b32_e32 v38, v4
	v_mov_b32_e32 v39, v4
	v_mov_b32_e32 v40, v4
	v_mov_b32_e32 v41, v4
	v_mov_b32_e32 v42, v4
	v_mov_b32_e32 v43, v4
	v_mov_b32_e32 v44, v4
	v_mov_b32_e32 v45, v4
	v_mov_b32_e32 v46, v4
	v_mov_b32_e32 v47, v4
	v_mov_b32_e32 v48, v4
	v_mov_b32_e32 v49, v4
	v_mov_b32_e32 v50, v4
	v_mov_b32_e32 v51, v4
	v_mov_b32_e32 v52, v4
	v_mov_b32_e32 v53, v4
	v_mov_b32_e32 v54, v4
	v_mov_b32_e32 v55, v4
	v_mov_b32_e32 v56, v4
	v_mov_b32_e32 v57, v4
	v_mov_b32_e32 v58, v4
	v_mov_b32_e32 v59, v4
	v_mov_b32_e32 v60, v4
	v_mov_b32_e32 v61, v4
	v_mov_b32_e32 v62, v4
	v_mov_b32_e32 v63, v4
	v_mov_b32_e32 v64, v4
	v_mov_b32_e32 v65, v4
	v_mov_b32_e32 v66, v4
	v_mov_b32_e32 v67, v4
	v_mov_b32_e32 v68, v4
	v_mov_b32_e32 v69, v4
	v_mov_b32_e32 v70, v4
	v_mov_b32_e32 v71, v4
	v_mov_b32_e32 v72, v4
	v_mov_b32_e32 v73, v4
	v_mov_b32_e32 v74, v4
	v_mov_b32_e32 v75, v4
	v_mov_b32_e32 v76, v4
	v_mov_b32_e32 v77, v4
	v_mov_b32_e32 v78, v4
	v_mov_b32_e32 v79, v4
	v_mov_b32_e32 v80, v4
	v_mov_b32_e32 v81, v4
	v_mov_b32_e32 v82, v4
	v_mov_b32_e32 v83, v4
	v_mov_b32_e32 v84, v4
	v_mov_b32_e32 v85, v4
	v_mov_b32_e32 v86, v4
	v_mov_b32_e32 v87, v4
	v_mov_b32_e32 v88, v4
	v_mov_b32_e32 v89, v4
	v_mov_b32_e32 v90, v4
	v_mov_b32_e32 v91, v4
	v_mov_b32_e32 v92, v4
	v_mov_b32_e32 v93, v4
	v_mov_b32_e32 v94, v4
	v_mov_b32_e32 v95, v4
	v_mov_b32_e32 v96, v4
	v_mov_b32_e32 v97, v4
	v_mov_b32_e32 v98, v4
	v_mov_b32_e32 v99, v4
	v_mov_b32_e32 v100, v4
	v_mov_b32_e32 v101, v4
	v_mov_b32_e32 v102, v4
	v_mov_b32_e32 v103, v4
	v_mov_b32_e32 v104, v4
	v_mov_b32_e32 v105, v4
	v_mov_b32_e32 v106, v4
	v_mov_b32_e32 v107, v4
	v_mov_b32_e32 v108, v4
	v_mov_b32_e32 v109, v4
	v_mov_b32_e32 v110, v4
	v_mov_b32_e32 v111, v4
	v_mov_b32_e32 v112, v4
	v_mov_b32_e32 v113, v4
	v_mov_b32_e32 v114, v4
	v_mov_b32_e32 v115, v4
	v_mov_b32_e32 v116, v4
	v_mov_b32_e32 v117, v4
	v_mov_b32_e32 v118, v4
	v_mov_b32_e32 v119, v4
	v_mov_b32_e32 v120, v4
	v_mov_b32_e32 v121, v4
	v_mov_b32_e32 v122, v4
	v_mov_b32_e32 v123, v4
	v_mov_b32_e32 v124, v4
	v_mov_b32_e32 v125, v4
	v_mov_b32_e32 v126, v4
	v_mov_b32_e32 v127, v4
	v_mov_b32_e32 v128, v4
	v_mov_b32_e32 v129, v4
	v_mov_b32_e32 v130, v4
	v_mov_b32_e32 v131, v4
	s_mov_b64 s[36:37], 0x3020080
	s_mov_b64 s[38:39], 0xc9a0100
	s_mov_b64 s[40:41], 0x3000100
	s_mov_b64 s[42:43], 0xc9c0100
	s_mov_b64 s[44:45], 0x3020100
	s_mov_b64 s[46:47], 0xc9a0180
	s_mov_b64 s[48:49], 0x3000180
	s_mov_b64 s[50:51], 0xc9c0180
	s_waitcnt vmcnt(6)
	s_barrier

; DI int tid_opaque() { int t = threadIdx.x; asm volatile("" : "+v"(t)); return t; }
;   constexpr int HT = 128 * 64;
;   bf16_t* shm = (bf16_t*)smem;
;   const int t = tid_opaque();
.LBB0_1258:
	s_or_b64 exec, exec, s[8:9]
	v_add_u32_e32 v0, v150, v0
	v_and_b32_e32 v0, 0xfffffc00, v0
	v_sub_u32_e32 v0, v150, v0
	v_lshrrev_b32_e32 v6, 4, v0
	v_add_u32_e32 v1, v3, v1
	v_bitop3_b32 v7, v6, v0, 32 bitop3:0x6c
	v_ashrrev_i32_e32 v0, 31, v0
	v_ashrrev_i32_e32 v1, 6, v1
	v_lshrrev_b32_e32 v0, 26, v0
	v_lshlrev_b32_e32 v6, 3, v1
	v_add_u32_e32 v0, v7, v0
	v_and_b32_e32 v6, -16, v6
	v_ashrrev_i32_e32 v0, 6, v0
	s_and_b32 s1, s12, 63
	s_and_b32 s8, s20, 0xffffff00
	v_add_u32_e32 v6, v0, v6
	v_mul_i32_i24_e32 v0, 64, v0
	s_lshl_b32 s12, s1, 19
	s_ashr_i32 s9, s8, 31
	s_ashr_i32 s1, s0, 31
	v_lshlrev_b32_e32 v1, 5, v1
	v_sub_u32_e32 v0, v7, v0
	v_mov_b32_e32 v13, 1
	s_lshl_b64 s[14:15], s[8:9], 11
	s_lshl_b64 s[8:9], s[0:1], 11
	v_and_b32_e32 v1, 32, v1
	v_ashrrev_i16_sdwa v0, v13, sext(v0) dst_sel:DWORD dst_unused:UNUSED_PAD src0_sel:DWORD src1_sel:BYTE_0
	s_add_u32 s8, s4, s8
	v_add_u32_sdwa v0, v1, sext(v0) dst_sel:DWORD dst_unused:UNUSED_PAD src0_sel:DWORD src1_sel:WORD_0
	v_ashrrev_i32_e32 v7, 31, v6
	v_readlane_b32 s40, v254, 35
	s_addc_u32 s9, s5, s9
	v_lshlrev_b64 v[132:133], 11, v[6:7]
	v_ashrrev_i32_e32 v1, 31, v0
	v_readlane_b32 s41, v254, 36
	v_lshl_add_u64 v[6:7], s[8:9], 0, v[132:133]
	v_lshlrev_b64 v[8:9], 1, v[0:1]
	v_add_u32_e32 v164, 0x18000, v150
	s_mov_b32 s13, s40
	v_lshl_add_u64 v[6:7], v[6:7], 0, v[8:9]
	s_mov_b64 s[40:41], 0x80
	v_readfirstlane_b32 s1, v164
	v_lshl_add_u64 v[6:7], v[6:7], 0, s[40:41]
	s_mov_b32 m0, s1
	s_waitcnt vmcnt(4)
	s_barrier
	global_load_lds_dwordx4 v[6:7], off
	v_ashrrev_i32_e32 v6, 31, v152
	v_lshrrev_b32_e32 v6, 22, v6
	v_add_u32_e32 v6, v152, v6
	v_ashrrev_i32_e32 v7, 10, v6
	v_mul_i32_i24_e32 v6, 0x400, v7
	v_sub_u32_e32 v6, v152, v6
	v_lshrrev_b32_e32 v10, 4, v6
	v_bitop3_b32 v10, v10, v6, 32 bitop3:0x6c
	v_ashrrev_i32_e32 v11, 31, v10
	v_lshrrev_b32_e32 v11, 26, v11
	v_add_u32_e32 v11, v10, v11
	v_lshlrev_b32_e32 v6, 3, v7
	v_ashrrev_i32_e32 v12, 6, v11
	v_and_b32_e32 v11, 0xc0, v11
	v_and_b32_e32 v6, -16, v6
	v_lshlrev_b32_e32 v7, 5, v7
	v_sub_u32_e32 v10, v10, v11
	v_add_u32_e32 v6, v12, v6
	v_and_b32_e32 v7, 32, v7
	v_ashrrev_i16_sdwa v10, v13, sext(v10) dst_sel:DWORD dst_unused:UNUSED_PAD src0_sel:DWORD src1_sel:BYTE_0
	v_add_u32_sdwa v134, v7, sext(v10) dst_sel:DWORD dst_unused:UNUSED_PAD src0_sel:DWORD src1_sel:WORD_0
	v_ashrrev_i32_e32 v7, 31, v6
	v_add_u32_e32 v165, 0x1a000, v150
	v_lshlrev_b64 v[136:137], 11, v[6:7]
	v_ashrrev_i32_e32 v135, 31, v134
	v_readfirstlane_b32 s1, v165
	v_lshl_add_u64 v[6:7], s[8:9], 0, v[136:137]
	v_lshlrev_b64 v[10:11], 1, v[134:135]
	s_mov_b32 m0, s1
	s_lshl_b32 s1, s27, 11
	v_lshl_add_u64 v[6:7], v[6:7], 0, v[10:11]
	s_waitcnt lgkmcnt(0)
; #define LDA8(dst, b, h) _Pragma("unroll") for (int m = 0; m < 4; ++m) _Pragma("unroll") for (int k = 0; k < 2; ++k) \
;     dst[m][k] = *(const bf16x8*)((const char*)SA8(b, h) + lds_byte8(wr * 64 + m * 16 + fr, k * 32 + fq * 8))
; #define LDB8(dst, b, h) _Pragma("unroll") for (int n = 0; n < 2; ++n) _Pragma("unroll") for (int k = 0; k < 2; ++k) \
;     dst[n][k] = *(const bf16x8*)((const char*)SB8(b, h) + lds_byte8(wc * 32 + n * 16 + fr, k * 32 + fq * 8))
; #define WAIT_V8(n) asm volatile("s_waitcnt vmcnt(" #n ")" ::: "memory")
; #define BAR8 __builtin_amdgcn_s_barrier()
; #define SCHED8 __builtin_amdgcn_sched_barrier(0)
;     ...
;   const int brow = m0, bcol = n0;
;   const int wid = t >> 6, lane = t & 63, wr = wid >> 2, wc = wid & 3, fr = lane & 15, fq = lane >> 4;
;   f32x4 acc[2][2][4][2];
;   {
;     float zinit = 0.f;
;     asm volatile("" : "+v"(zinit));
; #pragma unroll
;     for (int a = 0; a < 2; ++a)
; #pragma unroll
;       for (int b = 0; b < 2; ++b)
; #pragma unroll
;         for (int m = 0; m < 4; ++m)
; #pragma unroll
;           for (int n = 0; n < 2; ++n)
; #pragma unroll
;             for (int j = 0; j < 4; ++j) acc[a][b][m][n][j] = zinit;
;   }
;   bf16x8 At[4][2], B0[2][2], B1[2][2];
;   const int nt = K / 64;
;   if (!pre) {
;     STAGE8(SB8(0, 0), Bt, K, bcol, 0); STAGE8(SA8(0, 0), A, lda, brow, 0);
;     STAGE8(SB8(0, 1), Bt, K, bcol + 128, 0); STAGE8(SA8(0, 1), A, lda, brow + 128, 0);
;   }
;   if (wr == 1) BAR8;
;   WAIT_V8(4); BAR8;
;   STAGE8(SB8(1, 0), Bt, K, bcol, 1); STAGE8(SA8(1, 0), A, lda, brow, 1); STAGE8(SB8(1, 1), Bt, K, bcol + 128, 1);
;   WAIT_V8(6); BAR8;
;   for (int tt = 0; tt < nt - 2; tt += 2) {
;     LDB8(B0, 0, 0); SCHED8; LDA8(At, 0, 0); STAGE8(SA8(1, 1), A, lda, brow + 128, tt + 1);
	s_add_u32 s8, s2, s1
	v_lshl_add_u64 v[6:7], v[6:7], 0, s[40:41]
	s_addc_u32 s9, s3, 0
	global_load_lds_dwordx4 v[6:7], off
	v_lshl_add_u64 v[6:7], s[8:9], 0, v[132:133]
	v_add_u32_e32 v166, 0x8000, v150
	v_lshl_add_u64 v[6:7], v[6:7], 0, v[8:9]
	v_readfirstlane_b32 s1, v166
	s_or_b32 s36, s0, 0x80
	v_lshl_add_u64 v[6:7], v[6:7], 0, s[40:41]
	s_mov_b32 m0, s1
	s_ashr_i32 s37, s36, 31
	global_load_lds_dwordx4 v[6:7], off
	v_lshl_add_u64 v[6:7], s[8:9], 0, v[136:137]
	v_add_u32_e32 v167, 0xa000, v150
	s_lshl_b64 s[36:37], s[36:37], 11
	v_lshl_add_u64 v[6:7], v[6:7], 0, v[10:11]
	v_readfirstlane_b32 s1, v167
	s_add_u32 s36, s4, s36
	v_lshl_add_u64 v[6:7], v[6:7], 0, s[40:41]
	s_mov_b32 m0, s1
	s_addc_u32 s37, s5, s37
	global_load_lds_dwordx4 v[6:7], off
	v_lshl_add_u64 v[6:7], s[36:37], 0, v[132:133]
	v_add_u32_e32 v168, 0x1c000, v150
	v_lshl_add_u64 v[6:7], v[6:7], 0, v[8:9]
	v_readfirstlane_b32 s1, v168
	v_lshl_add_u64 v[6:7], v[6:7], 0, s[40:41]
	s_mov_b32 m0, s1
	v_add_u32_e32 v170, 0x1e000, v150
	global_load_lds_dwordx4 v[6:7], off
	v_lshl_add_u64 v[6:7], s[36:37], 0, v[136:137]
	v_lshl_add_u64 v[6:7], v[6:7], 0, v[10:11]
	v_readfirstlane_b32 s1, v170
	v_lshl_add_u64 v[6:7], v[6:7], 0, s[40:41]
	s_mov_b32 m0, s1
	v_and_b32_e32 v147, 15, v3
	global_load_lds_dwordx4 v[6:7], off
	v_bfe_u32 v148, v3, 4, 2
	v_lshlrev_b32_e32 v6, 4, v148
	v_lshlrev_b32_e32 v7, 6, v147
	v_lshlrev_b32_e32 v14, 2, v3
	v_or_b32_e32 v13, v6, v7
	v_and_b32_e32 v14, 32, v14
	s_mov_b32 s1, 0x10000
	v_bitop3_b32 v16, v13, s1, v14 bitop3:0xde
	s_mov_b32 s1, 0x14000
	v_bitop3_b32 v15, v6, v14, v7 bitop3:0x36
	v_bitop3_b32 v17, v13, s1, v14 bitop3:0xde
	s_mov_b32 s1, 0x18000
	v_lshlrev_b32_e32 v7, 6, v3
	v_bitop3_b32 v18, v13, s1, v14 bitop3:0xde
	s_mov_b32 s1, 0x1c000
	v_and_b32_e32 v7, 0x3c0, v7
	v_bitop3_b32 v13, v13, s1, v14 bitop3:0xde
	v_bitop3_b32 v14, v7, v14, v6 bitop3:0x36
	v_lshl_add_u64 v[6:7], s[12:13], 0, v[132:133]
	v_lshl_add_u64 v[6:7], v[6:7], 0, v[8:9]
	v_lshl_add_u64 v[138:139], s[2:3], 0, v[6:7]
	v_lshl_add_u64 v[6:7], s[12:13], 0, v[136:137]
	v_lshl_add_u64 v[6:7], v[6:7], 0, v[10:11]
	v_lshl_add_u64 v[140:141], s[2:3], 0, v[6:7]
	v_lshl_add_u64 v[6:7], s[14:15], 0, v[132:133]
	v_lshl_add_u64 v[6:7], v[6:7], 0, v[8:9]
	v_bfe_u32 v146, v3, 6, 2
	v_lshlrev_b32_e32 v149, 6, v5
	v_lshlrev_b32_e32 v5, 13, v5
	v_lshl_add_u64 v[142:143], s[6:7], 0, v[6:7]
	v_lshl_add_u64 v[6:7], s[14:15], 0, v[136:137]
	v_readlane_b32 s42, v254, 37
	v_readlane_b32 s43, v254, 38
	v_lshlrev_b32_e32 v12, 12, v146
	v_or_b32_e32 v19, 0x800, v5
	v_or_b32_e32 v20, 0x1000, v5
	v_or_b32_e32 v21, 0x1800, v5
	v_lshl_add_u64 v[6:7], v[6:7], 0, v[10:11]
	v_lshl_add_u64 v[144:145], s[6:7], 0, v[6:7]
	s_mov_b32 s1, -2
	s_mov_b64 s[12:13], 0
	v_add_u32_e32 v171, v16, v12
	v_add_u32_e32 v161, v15, v5
	v_add_u32_e32 v160, v14, v19
	v_add_u32_e32 v159, v14, v20
	v_add_u32_e32 v158, v14, v21
	v_add_u32_e32 v169, v17, v12
	v_add_u32_e32 v163, v18, v12
	v_add_u32_e32 v162, v13, v12
	v_mov_b32_e32 v5, v4
	v_mov_b32_e32 v6, v4
	v_mov_b32_e32 v7, v4
	v_mov_b32_e32 v8, v4
	v_mov_b32_e32 v9, v4
	v_mov_b32_e32 v10, v4
	v_mov_b32_e32 v11, v4
	v_mov_b32_e32 v12, v4
	v_mov_b32_e32 v13, v4
	v_mov_b32_e32 v14, v4
	v_mov_b32_e32 v15, v4
	v_mov_b32_e32 v16, v4
	v_mov_b32_e32 v17, v4
	v_mov_b32_e32 v18, v4
	v_mov_b32_e32 v19, v4
	v_mov_b32_e32 v20, v4
	v_mov_b32_e32 v21, v4
	v_mov_b32_e32 v22, v4
	v_mov_b32_e32 v23, v4
	v_mov_b32_e32 v24, v4
	v_mov_b32_e32 v25, v4
	v_mov_b32_e32 v26, v4
	v_mov_b32_e32 v27, v4
	v_mov_b32_e32 v28, v4
	v_mov_b32_e32 v29, v4
	v_mov_b32_e32 v30, v4
	v_mov_b32_e32 v31, v4
	v_mov_b32_e32 v32, v4
	v_mov_b32_e32 v33, v4
	v_mov_b32_e32 v34, v4
	v_mov_b32_e32 v35, v4
	v_mov_b32_e32 v36, v4
	v_mov_b32_e32 v37, v4
	v_mov_b32_e32 v38, v4
	v_mov_b32_e32 v39, v4
	v_mov_b32_e32 v40, v4
	v_mov_b32_e32 v41, v4
	v_mov_b32_e32 v42, v4
	v_mov_b32_e32 v43, v4
	v_mov_b32_e32 v44, v4
	v_mov_b32_e32 v45, v4
	v_mov_b32_e32 v46, v4
	v_mov_b32_e32 v47, v4
	v_mov_b32_e32 v48, v4
	v_mov_b32_e32 v49, v4
	v_mov_b32_e32 v50, v4
	v_mov_b32_e32 v51, v4
	v_mov_b32_e32 v52, v4
	v_mov_b32_e32 v53, v4
	v_mov_b32_e32 v54, v4
	v_mov_b32_e32 v55, v4
	v_mov_b32_e32 v56, v4
	v_mov_b32_e32 v57, v4
	v_mov_b32_e32 v58, v4
	v_mov_b32_e32 v59, v4
	v_mov_b32_e32 v60, v4
	v_mov_b32_e32 v61, v4
	v_mov_b32_e32 v62, v4
	v_mov_b32_e32 v63, v4
	v_mov_b32_e32 v64, v4
	v_mov_b32_e32 v65, v4
	v_mov_b32_e32 v66, v4
	v_mov_b32_e32 v67, v4
	v_mov_b32_e32 v68, v4
	v_mov_b32_e32 v69, v4
	v_mov_b32_e32 v70, v4
	v_mov_b32_e32 v71, v4
	v_mov_b32_e32 v72, v4
	v_mov_b32_e32 v73, v4
	v_mov_b32_e32 v74, v4
	v_mov_b32_e32 v75, v4
	v_mov_b32_e32 v76, v4
	v_mov_b32_e32 v77, v4
	v_mov_b32_e32 v78, v4
	v_mov_b32_e32 v79, v4
	v_mov_b32_e32 v80, v4
	v_mov_b32_e32 v81, v4
	v_mov_b32_e32 v82, v4
	v_mov_b32_e32 v83, v4
	v_mov_b32_e32 v84, v4
	v_mov_b32_e32 v85, v4
	v_mov_b32_e32 v86, v4
	v_mov_b32_e32 v87, v4
	v_mov_b32_e32 v88, v4
	v_mov_b32_e32 v89, v4
	v_mov_b32_e32 v90, v4
	v_mov_b32_e32 v91, v4
	v_mov_b32_e32 v92, v4
	v_mov_b32_e32 v93, v4
	v_mov_b32_e32 v94, v4
	v_mov_b32_e32 v95, v4
	v_mov_b32_e32 v96, v4
	v_mov_b32_e32 v97, v4
	v_mov_b32_e32 v98, v4
	v_mov_b32_e32 v99, v4
	v_mov_b32_e32 v100, v4
	v_mov_b32_e32 v101, v4
	v_mov_b32_e32 v102, v4
	v_mov_b32_e32 v103, v4
	v_mov_b32_e32 v104, v4
	v_mov_b32_e32 v105, v4
	v_mov_b32_e32 v106, v4
	v_mov_b32_e32 v107, v4
	v_mov_b32_e32 v108, v4
	v_mov_b32_e32 v109, v4
	v_mov_b32_e32 v110, v4
	v_mov_b32_e32 v111, v4
	v_mov_b32_e32 v112, v4
	v_mov_b32_e32 v113, v4
	v_mov_b32_e32 v114, v4
	v_mov_b32_e32 v115, v4
	v_mov_b32_e32 v116, v4
	v_mov_b32_e32 v117, v4
	v_mov_b32_e32 v118, v4
	v_mov_b32_e32 v119, v4
	v_mov_b32_e32 v120, v4
	v_mov_b32_e32 v121, v4
	v_mov_b32_e32 v122, v4
	v_mov_b32_e32 v123, v4
	v_mov_b32_e32 v124, v4
	v_mov_b32_e32 v125, v4
	v_mov_b32_e32 v126, v4
	v_mov_b32_e32 v127, v4
	v_mov_b32_e32 v128, v4
	v_mov_b32_e32 v129, v4
	v_mov_b32_e32 v130, v4
	v_mov_b32_e32 v131, v4
	s_mov_b64 s[36:37], 0xcaa0100
	s_mov_b64 s[40:41], 0xcae0100
	s_mov_b64 s[42:43], 0xcaa0180
	s_mov_b64 s[44:45], 0xcae0180
	s_mov_b64 s[100:101], 0x40180
	v_add_u32_e32 v174, 0xc000, v150
	v_add_u32_e32 v175, 0xe000, v150
	v_lshl_add_u64 v[222:223], v[138:139], 0, s[34:35]
	v_readfirstlane_b32 s14, v174
	s_mov_b32 m0, s14
	v_readfirstlane_b32 s14, v175
	global_load_lds_dwordx4 v[222:223], off
	v_lshl_add_u64 v[222:223], v[140:141], 0, s[34:35]
	s_mov_b32 m0, s14
	s_nop 0
	global_load_lds_dwordx4 v[222:223], off
	s_waitcnt vmcnt(8)
	s_barrier

; #define WAIT_V8(n) asm volatile("s_waitcnt vmcnt(" #n ")" ::: "memory")
; #define BAR8 __builtin_amdgcn_s_barrier()
;     ...
;   const int brow = m0, bcol = n0;
;   const int wid = t >> 6, lane = t & 63, wr = wid >> 2, wc = wid & 3, fr = lane & 15, fq = lane >> 4;
;   f32x4 acc[2][2][4][2];
;   {
;     float zinit = 0.f;
;     asm volatile("" : "+v"(zinit));
; #pragma unroll
;     for (int a = 0; a < 2; ++a)
; #pragma unroll
;       for (int b = 0; b < 2; ++b)
; #pragma unroll
;         for (int m = 0; m < 4; ++m)
; #pragma unroll
;           for (int n = 0; n < 2; ++n)
; #pragma unroll
;             for (int j = 0; j < 4; ++j) acc[a][b][m][n][j] = zinit;
;   }
;   bf16x8 At[4][2], B0[2][2], B1[2][2];
;   const int nt = K / 64;
;   if (!pre) {
;     STAGE8(SB8(0, 0), Bt, K, bcol, 0); STAGE8(SA8(0, 0), A, lda, brow, 0);
;     STAGE8(SB8(0, 1), Bt, K, bcol + 128, 0); STAGE8(SA8(0, 1), A, lda, brow + 128, 0);
;   }
;   if (wr == 1) BAR8;
;   WAIT_V8(4); BAR8;
;   STAGE8(SB8(1, 0), Bt, K, bcol, 1); STAGE8(SA8(1, 0), A, lda, brow, 1); STAGE8(SB8(1, 1), Bt, K, bcol + 128, 1);
;   WAIT_V8(6); BAR8;
.LBB0_1324:
	s_or_b64 exec, exec, s[12:13]
	v_add_u32_e32 v164, 0x18000, v150
	s_mov_b64 s[36:37], 0x80
	v_readfirstlane_b32 s12, v164
	v_add_u32_e32 v165, 0x1a000, v150
	v_lshl_add_u64 v[10:11], v[10:11], 0, s[36:37]
	s_mov_b32 m0, s12
	v_readfirstlane_b32 s12, v165
	v_add_u32_e32 v166, 0x8000, v150
	s_waitcnt vmcnt(4)
	s_barrier
	global_load_lds_dwordx4 v[10:11], off
	v_lshl_add_u64 v[10:11], v[12:13], 0, s[36:37]
	s_mov_b32 m0, s12
	v_readfirstlane_b32 s12, v166
	v_add_u32_e32 v167, 0xa000, v150
	global_load_lds_dwordx4 v[10:11], off
	v_lshl_add_u64 v[10:11], v[14:15], 0, s[36:37]
	s_mov_b32 m0, s12
	v_readfirstlane_b32 s12, v167
	v_add_u32_e32 v168, 0x1c000, v150
	global_load_lds_dwordx4 v[10:11], off
	v_lshl_add_u64 v[10:11], v[16:17], 0, s[36:37]
	s_mov_b32 m0, s12
	v_readfirstlane_b32 s12, v168
	v_add_u32_e32 v170, 0x1e000, v150
	global_load_lds_dwordx4 v[10:11], off
	v_lshl_add_u64 v[10:11], v[18:19], 0, s[36:37]
	s_mov_b32 m0, s12
	v_readfirstlane_b32 s12, v170
	global_load_lds_dwordx4 v[10:11], off
	v_lshl_add_u64 v[10:11], v[20:21], 0, s[36:37]
	s_mov_b32 m0, s12
	v_and_b32_e32 v147, 15, v3
	global_load_lds_dwordx4 v[10:11], off
	v_bfe_u32 v148, v3, 4, 2
	v_lshlrev_b32_e32 v10, 4, v148
	v_lshlrev_b32_e32 v11, 6, v147
	v_lshlrev_b32_e32 v13, 2, v3
	v_or_b32_e32 v12, v10, v11
	v_and_b32_e32 v13, 32, v13
	s_mov_b32 s12, 0x10000
	v_bitop3_b32 v18, v12, s12, v13 bitop3:0xde
	s_mov_b32 s12, 0x14000
	v_bitop3_b32 v17, v10, v13, v11 bitop3:0x36
	v_bitop3_b32 v19, v12, s12, v13 bitop3:0xde
	s_mov_b32 s12, 0x18000
	v_lshlrev_b32_e32 v11, 6, v3
	v_bitop3_b32 v20, v12, s12, v13 bitop3:0xde
	s_mov_b32 s12, 0x1c000
	v_and_b32_e32 v11, 0x3c0, v11
	s_movk_i32 s31, 0x1600
	s_and_b32 s29, s21, 0xffffff00
	v_bitop3_b32 v21, v12, s12, v13 bitop3:0xde
	v_bitop3_b32 v24, v11, v13, v10 bitop3:0x36
	v_mad_i64_i32 v[10:11], s[12:13], v5, s31, 0
	v_mov_b32_e32 v5, 0x1600
	v_mad_i64_i32 v[12:13], s[12:13], s29, v5, v[10:11]
	v_lshl_add_u64 v[12:13], v[12:13], 0, v[6:7]
	v_lshl_add_u64 v[138:139], s[4:5], 0, v[12:13]
	v_mad_i64_i32 v[12:13], s[12:13], v22, s31, 0
	v_mad_i64_i32 v[14:15], s[12:13], s29, v5, v[12:13]
	s_bfe_u32 s29, s20, 0x60008
	v_mov_b32_e32 v5, 0x160000
	v_mad_u64_u32 v[10:11], s[12:13], s29, v5, v[10:11]
	v_lshl_add_u64 v[6:7], v[10:11], 0, v[6:7]
	v_bfe_u32 v146, v3, 6, 2
	v_lshlrev_b32_e32 v149, 6, v23
	v_lshlrev_b32_e32 v23, 13, v23
	v_lshl_add_u64 v[142:143], s[2:3], 0, v[6:7]
	v_mad_u64_u32 v[6:7], s[12:13], s29, v5, v[12:13]
	v_lshlrev_b32_e32 v16, 12, v146
	v_or_b32_e32 v25, 0x800, v23
	v_or_b32_e32 v26, 0x1000, v23
	v_or_b32_e32 v27, 0x1800, v23
	v_lshl_add_u64 v[14:15], v[14:15], 0, v[8:9]
	v_lshl_add_u64 v[6:7], v[6:7], 0, v[8:9]
	s_ashr_i32 s9, s8, 31
	v_lshl_add_u64 v[140:141], s[4:5], 0, v[14:15]
	v_lshl_add_u64 v[144:145], s[2:3], 0, v[6:7]
	s_mov_b32 s29, -2
	s_mov_b64 s[12:13], 0
	v_add_u32_e32 v171, v18, v16
	v_add_u32_e32 v156, v17, v23
	v_add_u32_e32 v155, v24, v25
	v_add_u32_e32 v154, v24, v26
	v_add_u32_e32 v153, v24, v27
	v_add_u32_e32 v169, v19, v16
	v_add_u32_e32 v159, v20, v16
	v_add_u32_e32 v158, v21, v16
	v_mov_b32_e32 v5, v4
	v_mov_b32_e32 v6, v4
	v_mov_b32_e32 v7, v4
	v_mov_b32_e32 v8, v4
	v_mov_b32_e32 v9, v4
	v_mov_b32_e32 v10, v4
	v_mov_b32_e32 v11, v4
	v_mov_b32_e32 v12, v4
	v_mov_b32_e32 v13, v4
	v_mov_b32_e32 v14, v4
	v_mov_b32_e32 v15, v4
	v_mov_b32_e32 v16, v4
	v_mov_b32_e32 v17, v4
	v_mov_b32_e32 v18, v4
	v_mov_b32_e32 v19, v4
	v_mov_b32_e32 v20, v4
	v_mov_b32_e32 v21, v4
	v_mov_b32_e32 v22, v4
	v_mov_b32_e32 v23, v4
	v_mov_b32_e32 v24, v4
	v_mov_b32_e32 v25, v4
	v_mov_b32_e32 v26, v4
	v_mov_b32_e32 v27, v4
	v_mov_b32_e32 v28, v4
	v_mov_b32_e32 v29, v4
	v_mov_b32_e32 v30, v4
	v_mov_b32_e32 v31, v4
	v_mov_b32_e32 v32, v4
	v_mov_b32_e32 v33, v4
	v_mov_b32_e32 v34, v4
	v_mov_b32_e32 v35, v4
	v_mov_b32_e32 v36, v4
	v_mov_b32_e32 v37, v4
	v_mov_b32_e32 v38, v4
	v_mov_b32_e32 v39, v4
	v_mov_b32_e32 v40, v4
	v_mov_b32_e32 v41, v4
	v_mov_b32_e32 v42, v4
	v_mov_b32_e32 v43, v4
	v_mov_b32_e32 v44, v4
	v_mov_b32_e32 v45, v4
	v_mov_b32_e32 v46, v4
	v_mov_b32_e32 v47, v4
	v_mov_b32_e32 v48, v4
	v_mov_b32_e32 v49, v4
	v_mov_b32_e32 v50, v4
	v_mov_b32_e32 v51, v4
	v_mov_b32_e32 v52, v4
	v_mov_b32_e32 v53, v4
	v_mov_b32_e32 v54, v4
	v_mov_b32_e32 v55, v4
	v_mov_b32_e32 v56, v4
	v_mov_b32_e32 v57, v4
	v_mov_b32_e32 v58, v4
	v_mov_b32_e32 v59, v4
	v_mov_b32_e32 v60, v4
	v_mov_b32_e32 v61, v4
	v_mov_b32_e32 v62, v4
	v_mov_b32_e32 v63, v4
	v_mov_b32_e32 v64, v4
	v_mov_b32_e32 v65, v4
	v_mov_b32_e32 v66, v4
	v_mov_b32_e32 v67, v4
	v_mov_b32_e32 v68, v4
	v_mov_b32_e32 v69, v4
	v_mov_b32_e32 v70, v4
	v_mov_b32_e32 v71, v4
	v_mov_b32_e32 v72, v4
	v_mov_b32_e32 v73, v4
	v_mov_b32_e32 v74, v4
	v_mov_b32_e32 v75, v4
	v_mov_b32_e32 v76, v4
	v_mov_b32_e32 v77, v4
	v_mov_b32_e32 v78, v4
	v_mov_b32_e32 v79, v4
	v_mov_b32_e32 v80, v4
	v_mov_b32_e32 v81, v4
	v_mov_b32_e32 v82, v4
	v_mov_b32_e32 v83, v4
	v_mov_b32_e32 v84, v4
	v_mov_b32_e32 v85, v4
	v_mov_b32_e32 v86, v4
	v_mov_b32_e32 v87, v4
	v_mov_b32_e32 v88, v4
	v_mov_b32_e32 v89, v4
	v_mov_b32_e32 v90, v4
	v_mov_b32_e32 v91, v4
	v_mov_b32_e32 v92, v4
	v_mov_b32_e32 v93, v4
	v_mov_b32_e32 v94, v4
	v_mov_b32_e32 v95, v4
	v_mov_b32_e32 v96, v4
	v_mov_b32_e32 v97, v4
	v_mov_b32_e32 v98, v4
	v_mov_b32_e32 v99, v4
	v_mov_b32_e32 v100, v4
	v_mov_b32_e32 v101, v4
	v_mov_b32_e32 v102, v4
	v_mov_b32_e32 v103, v4
	v_mov_b32_e32 v104, v4
	v_mov_b32_e32 v105, v4
	v_mov_b32_e32 v106, v4
	v_mov_b32_e32 v107, v4
	v_mov_b32_e32 v108, v4
	v_mov_b32_e32 v109, v4
	v_mov_b32_e32 v110, v4
	v_mov_b32_e32 v111, v4
	v_mov_b32_e32 v112, v4
	v_mov_b32_e32 v113, v4
	v_mov_b32_e32 v114, v4
	v_mov_b32_e32 v115, v4
	v_mov_b32_e32 v116, v4
	v_mov_b32_e32 v117, v4
	v_mov_b32_e32 v118, v4
	v_mov_b32_e32 v119, v4
	v_mov_b32_e32 v120, v4
	v_mov_b32_e32 v121, v4
	v_mov_b32_e32 v122, v4
	v_mov_b32_e32 v123, v4
	v_mov_b32_e32 v124, v4
	v_mov_b32_e32 v125, v4
	v_mov_b32_e32 v126, v4
	v_mov_b32_e32 v127, v4
	v_mov_b32_e32 v128, v4
	v_mov_b32_e32 v129, v4
	v_mov_b32_e32 v130, v4
	v_mov_b32_e32 v131, v4
	s_mov_b64 s[36:37], 0x20b0080
	s_mov_b64 s[38:39], 0xd5a0100
	s_mov_b64 s[40:41], 0x2000100
	s_mov_b64 s[42:43], 0xd650100
	s_mov_b64 s[44:45], 0x20b0100
	s_mov_b64 s[46:47], 0xd5a0180
	s_mov_b64 s[48:49], 0x2000180
	s_mov_b64 s[50:51], 0xd650180
	s_waitcnt vmcnt(6)
	s_barrier
